# out-projection fused residual epilogue: non-temporal (nt) hint on the 64 streaming f32 residual loads and the 88 16-byte stores (data not re-read for a whole layer)
# speedup vs baseline: 1.0163x; 1.0119x over previous
;     template <int B> DI void load(f32x4 (&xv)[2][4], int row0, int col0) const {
; #pragma unroll
;         for (int q = 0; q < 2; ++q)
; #pragma unroll
;             for (int bj = 0; bj < 2; ++bj) { const size_t off = (size_t)(row0 + (B >> 1) * 128 + (2 * (B & 1) + q) * 16) * DM + col0 + bj * 128;
;                 xv[q][bj * 2] = *(const f32x4*)(xin + off); xv[q][bj * 2 + 1] = *(const f32x4*)(xin + off + 16); }
;     }
;     template <int B> DI void proc(const f32x4 (&acc)[2][2][4][2], const f32x4 (&xv)[2][4], int row0, int col0, int pn, int wc, int fq, int lane_) const {
; #pragma unroll
;         for (int q = 0; q < 2; ++q) {
;             constexpr int ai = B >> 1; const int m = 2 * (B & 1) + q;
;             const int r = row0 + ai * 128 + m * 16;
;             float part = 0.f;
; #pragma unroll
;             for (int bj = 0; bj < 2; ++bj) {
;                 const size_t off = (size_t)r * DM + col0 + bj * 128;
;                 const f32x4 v0 = acc[ai][bj][m][0] + xv[q][bj * 2], v1 = acc[ai][bj][m][1] + xv[q][bj * 2 + 1];
;                 *(f32x4*)(xout + off) = v0; *(f32x4*)(xout + off + 16) = v1;
;                 if (XB) {
;                     *(u32x2*)(XB + off) = (u32x2){pk2(v0[0], v0[1]), pk2(v0[2], v0[3])};
;                     *(u32x2*)(XB + off + 16) = (u32x2){pk2(v1[0], v1[1]), pk2(v1[2], v1[3])};
;                     part += (v0[0] * v0[0] + v0[1] * v0[1]) + (v0[2] * v0[2] + v0[3] * v0[3]) + (v1[0] * v1[0] + v1[1] * v1[1]) + (v1[2] * v1[2] + v1[3] * v1[3]);
;                 }
;             }
;             if (XB) {
;                 part += shx(part, 16, lane_); part += shx(part, 32, lane_);
;                 if (fq == 0) ssq_next[(size_t)r * 16 + pn * 4 + wc] = part;
;             }
;         }
;     }
;     DI void operator()(const f32x4 (&acc)[2][2][4][2], const pg8::Unit& u, int wr, int wc, int, int) const {
;         const int lane_ = fresh_lane(), fr = lane_ & 15, fq = lane_ >> 4;
;         const int row0 = u.pm * 256 + wr * 64 + fr;
;         const int col0 = u.pn * 256 + wc * 32 + 4 * fq;
;         f32x4 xa[2][4], xb[2][4];
;         load<0>(xa, row0, col0); load<1>(xb, row0, col0);
;         proc<0>(acc, xa, row0, col0, u.pn, wc, fq, lane_); load<2>(xa, row0, col0);
;         proc<1>(acc, xb, row0, col0, u.pn, wc, fq, lane_); load<3>(xb, row0, col0);
;         proc<2>(acc, xa, row0, col0, u.pn, wc, fq, lane_);
.LBB0_531:
	s_add_u32 s30, s78, 0xffffff00
	s_addc_u32 s31, s79, -1
	s_andn2_b64 vcc, exec, s[4:5]
	s_cbranch_vccnz .LBB0_579
	s_lshl_b32 s4, s74, 8
	s_add_i32 s4, s4, s59
	v_mbcnt_lo_u32_b32 v192, -1, 0
	v_mbcnt_hi_u32_b32 v192, -1, v192
	s_lshl_b32 s30, s73, 2
	v_and_or_b32 v210, v192, 15, s4
	s_lshl_b32 s4, s73, 8
	v_ashrrev_i32_e32 v130, 2, v192
	v_and_b32_e32 v130, -4, v130
	s_or_b32 s4, s4, s63
	v_add_u32_e32 v208, s4, v130
	v_ashrrev_i32_e32 v211, 31, v210
	v_ashrrev_i32_e32 v209, 31, v208
	v_lshlrev_b64 v[130:131], 10, v[210:211]
	v_lshl_add_u64 v[226:227], v[130:131], 0, v[208:209]
	v_lshlrev_b64 v[190:191], 2, v[226:227]
	v_or_b32_e32 v220, 16, v210
	v_lshl_add_u64 v[130:131], s[14:15], 0, v[190:191]
	v_ashrrev_i32_e32 v221, 31, v220
	global_load_dwordx4 v[186:189], v[130:131], off nt
	global_load_dwordx4 v[194:197], v[130:131], off offset:64 nt
	global_load_dwordx4 v[182:185], v[130:131], off offset:512 nt
	global_load_dwordx4 v[178:181], v[130:131], off offset:576 nt
	v_lshlrev_b64 v[130:131], 10, v[220:221]
	v_lshl_add_u64 v[222:223], v[130:131], 0, v[208:209]
	v_or_b32_e32 v216, 32, v210
	v_lshl_add_u64 v[130:131], v[222:223], 2, s[14:15]
	v_ashrrev_i32_e32 v217, 31, v216
	global_load_dwordx4 v[174:177], v[130:131], off nt
	global_load_dwordx4 v[170:173], v[130:131], off offset:64 nt
	global_load_dwordx4 v[166:169], v[130:131], off offset:512 nt
	global_load_dwordx4 v[162:165], v[130:131], off offset:576 nt
	v_lshlrev_b64 v[130:131], 10, v[216:217]
	v_lshl_add_u64 v[218:219], v[130:131], 0, v[208:209]
	v_or_b32_e32 v212, 48, v210
	v_lshl_add_u64 v[130:131], v[218:219], 2, s[14:15]
	v_ashrrev_i32_e32 v213, 31, v212
	global_load_dwordx4 v[158:161], v[130:131], off nt
	global_load_dwordx4 v[154:157], v[130:131], off offset:64 nt
	global_load_dwordx4 v[150:153], v[130:131], off offset:512 nt
	global_load_dwordx4 v[146:149], v[130:131], off offset:576 nt
	v_lshlrev_b64 v[130:131], 10, v[212:213]
	v_lshl_add_u64 v[214:215], v[130:131], 0, v[208:209]
	v_lshl_add_u64 v[130:131], v[214:215], 2, s[14:15]
	global_load_dwordx4 v[142:145], v[130:131], off nt
	global_load_dwordx4 v[138:141], v[130:131], off offset:64 nt
	global_load_dwordx4 v[134:137], v[130:131], off offset:512 nt
	s_nop 0
	global_load_dwordx4 v[130:133], v[130:131], off offset:576 nt
	v_cndmask_b32_e64 v193, 0, 1, s[8:9]
	v_lshlrev_b32_e32 v198, 2, v192
	s_mov_b64 s[34:35], -1
	v_cmp_gt_u32_e64 s[4:5], 16, v192
	s_ashr_i32 s31, s30, 31
	v_cmp_ne_u32_e64 s[6:7], 1, v193
	v_xor_b32_e32 v238, 64, v198
	v_xor_b32_e32 v237, 0x80, v198
	s_andn2_b64 vcc, exec, s[8:9]
	v_lshl_add_u64 v[224:225], s[48:49], 0, v[190:191]
	s_waitcnt vmcnt(0)
	v_pk_add_f32 v[192:193], v[128:129], v[188:189]
	v_pk_add_f32 v[190:191], v[126:127], v[186:187]
	v_pk_add_f32 v[188:189], v[124:125], v[196:197]
	v_pk_add_f32 v[186:187], v[122:123], v[194:195]
	v_pk_add_f32 v[126:127], v[118:119], v[182:183]
	v_pk_add_f32 v[122:123], v[114:115], v[178:179]
	global_store_dwordx4 v[224:225], v[190:193], off nt
	global_store_dwordx4 v[224:225], v[186:189], off offset:64 nt
	s_cbranch_vccnz .LBB0_536
	v_cvt_pk_bf16_f32 v114, v190, v191
	v_cvt_pk_bf16_f32 v115, v192, v193
	v_lshl_add_u64 v[118:119], v[226:227], 1, s[12:13]
	flat_store_dwordx2 v[118:119], v[114:115]
	v_cvt_pk_bf16_f32 v114, v186, v187
	v_cvt_pk_bf16_f32 v115, v188, v189
	flat_store_dwordx2 v[118:119], v[114:115] offset:32
	v_mul_f32_e32 v114, v191, v191
	v_mul_f32_e32 v115, v193, v193
	v_fmac_f32_e32 v114, v190, v190
	v_fmac_f32_e32 v115, v192, v192
	v_add_f32_e32 v114, v114, v115
	v_mul_f32_e32 v115, v187, v187
	v_pk_add_f32 v[128:129], v[120:121], v[184:185]
	v_fmac_f32_e32 v115, v186, v186
	v_mul_f32_e32 v178, v127, v127
	v_mul_f32_e32 v179, v129, v129
	v_add_f32_e32 v114, v114, v115
	v_mul_f32_e32 v115, v189, v189
	v_fmac_f32_e32 v178, v126, v126
	v_fmac_f32_e32 v179, v128, v128
	v_fmac_f32_e32 v115, v188, v188
	v_pk_add_f32 v[124:125], v[116:117], v[180:181]
	v_add_f32_e32 v178, v178, v179
	v_mul_f32_e32 v179, v123, v123
	v_add_f32_e32 v114, v115, v114
	v_mul_f32_e32 v115, v125, v125
	v_fmac_f32_e32 v179, v122, v122
	v_fmac_f32_e32 v115, v124, v124
	v_add_f32_e32 v178, v178, v179
	v_add_f32_e32 v115, v115, v178
	v_add_f32_e32 v114, v114, v115
	ds_bpermute_b32 v115, v238, v114
	global_store_dwordx4 v[224:225], v[126:129], off offset:512 nt
	global_store_dwordx4 v[224:225], v[122:125], off offset:576 nt
	v_cvt_pk_bf16_f32 v178, v126, v127
	v_cvt_pk_bf16_f32 v179, v128, v129
	v_cvt_pk_bf16_f32 v128, v122, v123
	s_waitcnt lgkmcnt(0)
	v_add_f32_e32 v114, v114, v115
	ds_bpermute_b32 v115, v237, v114
	v_cvt_pk_bf16_f32 v129, v124, v125
	flat_store_dwordx2 v[118:119], v[178:179] offset:256
	flat_store_dwordx2 v[118:119], v[128:129] offset:288
	s_and_saveexec_b64 s[34:35], s[4:5]
	s_cbranch_execz .LBB0_535
	v_lshlrev_b64 v[118:119], 6, v[210:211]
	v_lshl_add_u64 v[118:119], s[10:11], 0, v[118:119]
	v_lshl_add_u64 v[118:119], s[30:31], 2, v[118:119]
	s_lshl_b32 s92, s62, 2
	v_lshl_add_u64 v[118:119], v[118:119], 0, s[92:93]
	s_waitcnt lgkmcnt(0)
	v_add_f32_e32 v114, v114, v115
	flat_store_dword v[118:119], v114

; DI unsigned pk2(float lo, float hi) { f32x2 v = {lo, hi}; return __builtin_bit_cast(unsigned, __builtin_convertvector(v, bf2_t)); }
; DI float shx(float v, int m, int lane) { return __int_as_float(__builtin_amdgcn_ds_bpermute((lane ^ m) << 2, __float_as_int(v))); }
;     template <int B> DI void proc(const f32x4 (&acc)[2][2][4][2], const f32x4 (&xv)[2][4], int row0, int col0, int pn, int wc, int fq, int lane_) const {
;     ...
;             for (int bj = 0; bj < 2; ++bj) {
;                 const size_t off = (size_t)r * DM + col0 + bj * 128;
;                 const f32x4 v0 = acc[ai][bj][m][0] + xv[q][bj * 2], v1 = acc[ai][bj][m][1] + xv[q][bj * 2 + 1];
;                 *(f32x4*)(xout + off) = v0; *(f32x4*)(xout + off + 16) = v1;
;                 if (XB) {
;                     *(u32x2*)(XB + off) = (u32x2){pk2(v0[0], v0[1]), pk2(v0[2], v0[3])};
;                     *(u32x2*)(XB + off + 16) = (u32x2){pk2(v1[0], v1[1]), pk2(v1[2], v1[3])};
;                     part += (v0[0] * v0[0] + v0[1] * v0[1]) + (v0[2] * v0[2] + v0[3] * v0[3]) + (v1[0] * v1[0] + v1[1] * v1[1]) + (v1[2] * v1[2] + v1[3] * v1[3]);
;                 }
;             }
;             if (XB) {
;                 part += shx(part, 16, lane_); part += shx(part, 32, lane_);
;                 if (fq == 0) ssq_next[(size_t)r * 16 + pn * 4 + wc] = part;
;             }
;         }
.LBB0_536:
	s_andn2_b64 vcc, exec, s[34:35]
	s_cbranch_vccnz .LBB0_538
	v_pk_add_f32 v[128:129], v[120:121], v[184:185]
	v_pk_add_f32 v[124:125], v[116:117], v[180:181]
	global_store_dwordx4 v[224:225], v[126:129], off offset:512 nt
	global_store_dwordx4 v[224:225], v[122:125], off offset:576 nt
.LBB0_538:
	s_waitcnt lgkmcnt(0)
	v_pk_add_f32 v[114:115], v[112:113], v[176:177]
	v_pk_add_f32 v[112:113], v[110:111], v[174:175]
	v_pk_add_f32 v[118:119], v[108:109], v[172:173]
	v_pk_add_f32 v[116:117], v[106:107], v[170:171]
	v_lshl_add_u64 v[120:121], v[222:223], 2, s[48:49]
	s_mov_b64 s[34:35], -1
	s_and_b64 vcc, exec, s[6:7]
	v_pk_add_f32 v[110:111], v[102:103], v[166:167]
	v_pk_add_f32 v[106:107], v[98:99], v[162:163]
	global_store_dwordx4 v[120:121], v[112:115], off nt
	global_store_dwordx4 v[120:121], v[116:119], off offset:64 nt
	s_cbranch_vccnz .LBB0_542
	v_cvt_pk_bf16_f32 v98, v112, v113
	v_cvt_pk_bf16_f32 v99, v114, v115
	v_lshl_add_u64 v[102:103], v[222:223], 1, s[12:13]
	flat_store_dwordx2 v[102:103], v[98:99]
	v_cvt_pk_bf16_f32 v98, v116, v117
	v_cvt_pk_bf16_f32 v99, v118, v119
	flat_store_dwordx2 v[102:103], v[98:99] offset:32
	v_mul_f32_e32 v98, v113, v113
	v_mul_f32_e32 v99, v115, v115
	v_fmac_f32_e32 v98, v112, v112
	v_fmac_f32_e32 v99, v114, v114
	v_add_f32_e32 v98, v98, v99
	v_mul_f32_e32 v99, v117, v117
	v_pk_add_f32 v[112:113], v[104:105], v[168:169]
	v_fmac_f32_e32 v99, v116, v116
	v_mul_f32_e32 v114, v111, v111
	v_mul_f32_e32 v115, v113, v113
	v_add_f32_e32 v98, v98, v99
	v_mul_f32_e32 v99, v119, v119
	v_fmac_f32_e32 v114, v110, v110
	v_fmac_f32_e32 v115, v112, v112
	v_fmac_f32_e32 v99, v118, v118
	v_pk_add_f32 v[108:109], v[100:101], v[164:165]
	v_add_f32_e32 v114, v114, v115
	v_mul_f32_e32 v115, v107, v107
	v_add_f32_e32 v98, v99, v98
	v_mul_f32_e32 v99, v109, v109
	v_fmac_f32_e32 v115, v106, v106
	v_fmac_f32_e32 v99, v108, v108
	v_add_f32_e32 v114, v114, v115
	v_add_f32_e32 v99, v99, v114
	v_add_f32_e32 v98, v98, v99
	ds_bpermute_b32 v99, v238, v98
	global_store_dwordx4 v[120:121], v[110:113], off offset:512 nt
	global_store_dwordx4 v[120:121], v[106:109], off offset:576 nt
	v_cvt_pk_bf16_f32 v114, v110, v111
	v_cvt_pk_bf16_f32 v115, v112, v113
	v_cvt_pk_bf16_f32 v112, v106, v107
	s_waitcnt lgkmcnt(0)
	v_add_f32_e32 v98, v98, v99
	ds_bpermute_b32 v99, v237, v98
	v_cvt_pk_bf16_f32 v113, v108, v109
	flat_store_dwordx2 v[102:103], v[114:115] offset:256
	flat_store_dwordx2 v[102:103], v[112:113] offset:288
	s_and_saveexec_b64 s[34:35], s[4:5]
	s_cbranch_execz .LBB0_541
	v_lshlrev_b64 v[102:103], 6, v[220:221]
	v_lshl_add_u64 v[102:103], s[10:11], 0, v[102:103]
	v_lshl_add_u64 v[102:103], s[30:31], 2, v[102:103]
	s_lshl_b32 s92, s62, 2
	v_lshl_add_u64 v[102:103], v[102:103], 0, s[92:93]
	s_waitcnt lgkmcnt(0)
	v_add_f32_e32 v98, v98, v99
	flat_store_dword v[102:103], v98

; DI unsigned pk2(float lo, float hi) { f32x2 v = {lo, hi}; return __builtin_bit_cast(unsigned, __builtin_convertvector(v, bf2_t)); }
; DI float shx(float v, int m, int lane) { return __int_as_float(__builtin_amdgcn_ds_bpermute((lane ^ m) << 2, __float_as_int(v))); }
;     template <int B> DI void load(f32x4 (&xv)[2][4], int row0, int col0) const {
; #pragma unroll
;         for (int q = 0; q < 2; ++q)
; #pragma unroll
;             for (int bj = 0; bj < 2; ++bj) { const size_t off = (size_t)(row0 + (B >> 1) * 128 + (2 * (B & 1) + q) * 16) * DM + col0 + bj * 128;
;                 xv[q][bj * 2] = *(const f32x4*)(xin + off); xv[q][bj * 2 + 1] = *(const f32x4*)(xin + off + 16); }
;     }
;     template <int B> DI void proc(const f32x4 (&acc)[2][2][4][2], const f32x4 (&xv)[2][4], int row0, int col0, int pn, int wc, int fq, int lane_) const {
; #pragma unroll
;         for (int q = 0; q < 2; ++q) {
;             constexpr int ai = B >> 1; const int m = 2 * (B & 1) + q;
;             const int r = row0 + ai * 128 + m * 16;
;             float part = 0.f;
; #pragma unroll
;             for (int bj = 0; bj < 2; ++bj) {
;                 const size_t off = (size_t)r * DM + col0 + bj * 128;
;                 const f32x4 v0 = acc[ai][bj][m][0] + xv[q][bj * 2], v1 = acc[ai][bj][m][1] + xv[q][bj * 2 + 1];
;                 *(f32x4*)(xout + off) = v0; *(f32x4*)(xout + off + 16) = v1;
;                 if (XB) {
;                     *(u32x2*)(XB + off) = (u32x2){pk2(v0[0], v0[1]), pk2(v0[2], v0[3])};
;                     *(u32x2*)(XB + off + 16) = (u32x2){pk2(v1[0], v1[1]), pk2(v1[2], v1[3])};
;                     part += (v0[0] * v0[0] + v0[1] * v0[1]) + (v0[2] * v0[2] + v0[3] * v0[3]) + (v1[0] * v1[0] + v1[1] * v1[1]) + (v1[2] * v1[2] + v1[3] * v1[3]);
;                 }
;             }
;             if (XB) {
;                 part += shx(part, 16, lane_); part += shx(part, 32, lane_);
;                 if (fq == 0) ssq_next[(size_t)r * 16 + pn * 4 + wc] = part;
;             }
;         }
.LBB0_542:
	s_andn2_b64 vcc, exec, s[34:35]
	s_cbranch_vccnz .LBB0_544
	v_pk_add_f32 v[112:113], v[104:105], v[168:169]
	v_pk_add_f32 v[108:109], v[100:101], v[164:165]
	global_store_dwordx4 v[120:121], v[110:113], off offset:512 nt
	global_store_dwordx4 v[120:121], v[106:109], off offset:576 nt
.LBB0_544:
	v_add_u32_e32 v166, 0x80, v210
	v_ashrrev_i32_e32 v167, 31, v166
	s_waitcnt lgkmcnt(0)
	v_lshlrev_b64 v[98:99], 10, v[166:167]
	v_lshl_add_u64 v[168:169], v[98:99], 0, v[208:209]
	v_add_u32_e32 v162, 0x90, v210
	v_lshl_add_u64 v[98:99], v[168:169], 2, s[14:15]
	v_ashrrev_i32_e32 v163, 31, v162
	global_load_dwordx4 v[126:129], v[98:99], off nt
	global_load_dwordx4 v[122:125], v[98:99], off offset:64 nt
	global_load_dwordx4 v[118:121], v[98:99], off offset:512 nt
	global_load_dwordx4 v[114:117], v[98:99], off offset:576 nt
	v_lshlrev_b64 v[98:99], 10, v[162:163]
	v_lshl_add_u64 v[164:165], v[98:99], 0, v[208:209]
	v_lshl_add_u64 v[98:99], v[164:165], 2, s[14:15]
	global_load_dwordx4 v[110:113], v[98:99], off nt
	global_load_dwordx4 v[106:109], v[98:99], off offset:64 nt
	global_load_dwordx4 v[102:105], v[98:99], off offset:512 nt
	s_nop 0
	global_load_dwordx4 v[98:101], v[98:99], off offset:576 nt
	v_pk_add_f32 v[160:161], v[96:97], v[160:161]
	v_pk_add_f32 v[158:159], v[94:95], v[158:159]
	v_pk_add_f32 v[156:157], v[92:93], v[156:157]
	v_pk_add_f32 v[154:155], v[90:91], v[154:155]
	v_lshl_add_u64 v[170:171], v[218:219], 2, s[48:49]
	s_mov_b64 s[34:35], -1
	s_and_b64 vcc, exec, s[6:7]
	v_pk_add_f32 v[94:95], v[86:87], v[150:151]
	v_pk_add_f32 v[90:91], v[82:83], v[146:147]
	global_store_dwordx4 v[170:171], v[158:161], off nt
	global_store_dwordx4 v[170:171], v[154:157], off offset:64 nt
	s_cbranch_vccnz .LBB0_548
	v_cvt_pk_bf16_f32 v82, v158, v159
	v_cvt_pk_bf16_f32 v83, v160, v161
	v_lshl_add_u64 v[86:87], v[218:219], 1, s[12:13]
	flat_store_dwordx2 v[86:87], v[82:83]
	v_cvt_pk_bf16_f32 v82, v154, v155
	v_cvt_pk_bf16_f32 v83, v156, v157
	flat_store_dwordx2 v[86:87], v[82:83] offset:32
	v_mul_f32_e32 v82, v159, v159
	v_mul_f32_e32 v83, v161, v161
	v_fmac_f32_e32 v82, v158, v158
	v_fmac_f32_e32 v83, v160, v160
	v_add_f32_e32 v82, v82, v83
	v_mul_f32_e32 v83, v155, v155
	v_pk_add_f32 v[96:97], v[88:89], v[152:153]
	v_fmac_f32_e32 v83, v154, v154
	v_mul_f32_e32 v146, v95, v95
	v_mul_f32_e32 v147, v97, v97
	v_add_f32_e32 v82, v82, v83
	v_mul_f32_e32 v83, v157, v157
	v_fmac_f32_e32 v146, v94, v94
	v_fmac_f32_e32 v147, v96, v96
	v_fmac_f32_e32 v83, v156, v156
	v_pk_add_f32 v[92:93], v[84:85], v[148:149]
	v_add_f32_e32 v146, v146, v147
	v_mul_f32_e32 v147, v91, v91
	v_add_f32_e32 v82, v83, v82
	v_mul_f32_e32 v83, v93, v93
	v_fmac_f32_e32 v147, v90, v90
	v_fmac_f32_e32 v83, v92, v92
	v_add_f32_e32 v146, v146, v147
	v_add_f32_e32 v83, v83, v146
	v_add_f32_e32 v82, v82, v83
	ds_bpermute_b32 v83, v238, v82
	global_store_dwordx4 v[170:171], v[94:97], off offset:512 nt
	global_store_dwordx4 v[170:171], v[90:93], off offset:576 nt
	v_cvt_pk_bf16_f32 v146, v94, v95
	v_cvt_pk_bf16_f32 v147, v96, v97
	v_cvt_pk_bf16_f32 v96, v90, v91
	s_waitcnt lgkmcnt(0)
	v_add_f32_e32 v82, v82, v83
	ds_bpermute_b32 v83, v237, v82
	v_cvt_pk_bf16_f32 v97, v92, v93
	flat_store_dwordx2 v[86:87], v[146:147] offset:256
	flat_store_dwordx2 v[86:87], v[96:97] offset:288
	s_and_saveexec_b64 s[34:35], s[4:5]
	s_cbranch_execz .LBB0_547
	v_lshlrev_b64 v[86:87], 6, v[216:217]
	v_lshl_add_u64 v[86:87], s[10:11], 0, v[86:87]
	v_lshl_add_u64 v[86:87], s[30:31], 2, v[86:87]
	s_lshl_b32 s92, s62, 2
	v_lshl_add_u64 v[86:87], v[86:87], 0, s[92:93]
	s_waitcnt lgkmcnt(0)
	v_add_f32_e32 v82, v82, v83
	flat_store_dword v[86:87], v82

; DI unsigned pk2(float lo, float hi) { f32x2 v = {lo, hi}; return __builtin_bit_cast(unsigned, __builtin_convertvector(v, bf2_t)); }
; DI float shx(float v, int m, int lane) { return __int_as_float(__builtin_amdgcn_ds_bpermute((lane ^ m) << 2, __float_as_int(v))); }
;     template <int B> DI void proc(const f32x4 (&acc)[2][2][4][2], const f32x4 (&xv)[2][4], int row0, int col0, int pn, int wc, int fq, int lane_) const {
;     ...
;             for (int bj = 0; bj < 2; ++bj) {
;                 const size_t off = (size_t)r * DM + col0 + bj * 128;
;                 const f32x4 v0 = acc[ai][bj][m][0] + xv[q][bj * 2], v1 = acc[ai][bj][m][1] + xv[q][bj * 2 + 1];
;                 *(f32x4*)(xout + off) = v0; *(f32x4*)(xout + off + 16) = v1;
;                 if (XB) {
;                     *(u32x2*)(XB + off) = (u32x2){pk2(v0[0], v0[1]), pk2(v0[2], v0[3])};
;                     *(u32x2*)(XB + off + 16) = (u32x2){pk2(v1[0], v1[1]), pk2(v1[2], v1[3])};
;                     part += (v0[0] * v0[0] + v0[1] * v0[1]) + (v0[2] * v0[2] + v0[3] * v0[3]) + (v1[0] * v1[0] + v1[1] * v1[1]) + (v1[2] * v1[2] + v1[3] * v1[3]);
;                 }
;             }
;             if (XB) {
;                 part += shx(part, 16, lane_); part += shx(part, 32, lane_);
;                 if (fq == 0) ssq_next[(size_t)r * 16 + pn * 4 + wc] = part;
;             }
;         }
.LBB0_548:
	s_andn2_b64 vcc, exec, s[34:35]
	s_cbranch_vccnz .LBB0_550
	v_pk_add_f32 v[96:97], v[88:89], v[152:153]
	v_pk_add_f32 v[92:93], v[84:85], v[148:149]
	global_store_dwordx4 v[170:171], v[94:97], off offset:512 nt
	global_store_dwordx4 v[170:171], v[90:93], off offset:576 nt
.LBB0_550:
	s_waitcnt lgkmcnt(0)
	v_pk_add_f32 v[82:83], v[80:81], v[144:145]
	v_pk_add_f32 v[80:81], v[78:79], v[142:143]
	v_pk_add_f32 v[86:87], v[76:77], v[140:141]
	v_pk_add_f32 v[84:85], v[74:75], v[138:139]
	v_lshl_add_u64 v[88:89], v[214:215], 2, s[48:49]
	s_mov_b64 s[34:35], -1
	s_and_b64 vcc, exec, s[6:7]
	v_pk_add_f32 v[78:79], v[70:71], v[134:135]
	v_pk_add_f32 v[74:75], v[66:67], v[130:131]
	global_store_dwordx4 v[88:89], v[80:83], off nt
	global_store_dwordx4 v[88:89], v[84:87], off offset:64 nt
	s_cbranch_vccnz .LBB0_554
	v_cvt_pk_bf16_f32 v66, v80, v81
	v_cvt_pk_bf16_f32 v67, v82, v83
	v_lshl_add_u64 v[70:71], v[214:215], 1, s[12:13]
	flat_store_dwordx2 v[70:71], v[66:67]
	v_cvt_pk_bf16_f32 v66, v84, v85
	v_cvt_pk_bf16_f32 v67, v86, v87
	flat_store_dwordx2 v[70:71], v[66:67] offset:32
	v_mul_f32_e32 v66, v81, v81
	v_mul_f32_e32 v67, v83, v83
	v_fmac_f32_e32 v66, v80, v80
	v_fmac_f32_e32 v67, v82, v82
	v_add_f32_e32 v66, v66, v67
	v_mul_f32_e32 v67, v85, v85
	v_pk_add_f32 v[80:81], v[72:73], v[136:137]
	v_fmac_f32_e32 v67, v84, v84
	v_mul_f32_e32 v82, v79, v79
	v_mul_f32_e32 v83, v81, v81
	v_add_f32_e32 v66, v66, v67
	v_mul_f32_e32 v67, v87, v87
	v_fmac_f32_e32 v82, v78, v78
	v_fmac_f32_e32 v83, v80, v80
	v_fmac_f32_e32 v67, v86, v86
	v_pk_add_f32 v[76:77], v[68:69], v[132:133]
	v_add_f32_e32 v82, v82, v83
	v_mul_f32_e32 v83, v75, v75
	v_add_f32_e32 v66, v67, v66
	v_mul_f32_e32 v67, v77, v77
	v_fmac_f32_e32 v83, v74, v74
	v_fmac_f32_e32 v67, v76, v76
	v_add_f32_e32 v82, v82, v83
	v_add_f32_e32 v67, v67, v82
	v_add_f32_e32 v66, v66, v67
	ds_bpermute_b32 v67, v238, v66
	global_store_dwordx4 v[88:89], v[78:81], off offset:512 nt
	global_store_dwordx4 v[88:89], v[74:77], off offset:576 nt
	v_cvt_pk_bf16_f32 v82, v78, v79
	v_cvt_pk_bf16_f32 v83, v80, v81
	v_cvt_pk_bf16_f32 v80, v74, v75
	s_waitcnt lgkmcnt(0)
	v_add_f32_e32 v66, v66, v67
	ds_bpermute_b32 v67, v237, v66
	v_cvt_pk_bf16_f32 v81, v76, v77
	flat_store_dwordx2 v[70:71], v[82:83] offset:256
	flat_store_dwordx2 v[70:71], v[80:81] offset:288
	s_and_saveexec_b64 s[34:35], s[4:5]
	s_cbranch_execz .LBB0_553
	v_lshlrev_b64 v[70:71], 6, v[212:213]
	v_lshl_add_u64 v[70:71], s[10:11], 0, v[70:71]
	v_lshl_add_u64 v[70:71], s[30:31], 2, v[70:71]
	s_lshl_b32 s92, s62, 2
	v_lshl_add_u64 v[70:71], v[70:71], 0, s[92:93]
	s_waitcnt lgkmcnt(0)
	v_add_f32_e32 v66, v66, v67
	flat_store_dword v[70:71], v66

; DI unsigned pk2(float lo, float hi) { f32x2 v = {lo, hi}; return __builtin_bit_cast(unsigned, __builtin_convertvector(v, bf2_t)); }
; DI float shx(float v, int m, int lane) { return __int_as_float(__builtin_amdgcn_ds_bpermute((lane ^ m) << 2, __float_as_int(v))); }
;     template <int B> DI void load(f32x4 (&xv)[2][4], int row0, int col0) const {
; #pragma unroll
;         for (int q = 0; q < 2; ++q)
; #pragma unroll
;             for (int bj = 0; bj < 2; ++bj) { const size_t off = (size_t)(row0 + (B >> 1) * 128 + (2 * (B & 1) + q) * 16) * DM + col0 + bj * 128;
;                 xv[q][bj * 2] = *(const f32x4*)(xin + off); xv[q][bj * 2 + 1] = *(const f32x4*)(xin + off + 16); }
;     }
;     template <int B> DI void proc(const f32x4 (&acc)[2][2][4][2], const f32x4 (&xv)[2][4], int row0, int col0, int pn, int wc, int fq, int lane_) const {
; #pragma unroll
;         for (int q = 0; q < 2; ++q) {
;             constexpr int ai = B >> 1; const int m = 2 * (B & 1) + q;
;             const int r = row0 + ai * 128 + m * 16;
;             float part = 0.f;
; #pragma unroll
;             for (int bj = 0; bj < 2; ++bj) {
;                 const size_t off = (size_t)r * DM + col0 + bj * 128;
;                 const f32x4 v0 = acc[ai][bj][m][0] + xv[q][bj * 2], v1 = acc[ai][bj][m][1] + xv[q][bj * 2 + 1];
;                 *(f32x4*)(xout + off) = v0; *(f32x4*)(xout + off + 16) = v1;
;                 if (XB) {
;                     *(u32x2*)(XB + off) = (u32x2){pk2(v0[0], v0[1]), pk2(v0[2], v0[3])};
;                     *(u32x2*)(XB + off + 16) = (u32x2){pk2(v1[0], v1[1]), pk2(v1[2], v1[3])};
;                     part += (v0[0] * v0[0] + v0[1] * v0[1]) + (v0[2] * v0[2] + v0[3] * v0[3]) + (v1[0] * v1[0] + v1[1] * v1[1]) + (v1[2] * v1[2] + v1[3] * v1[3]);
;                 }
;             }
;             if (XB) {
;                 part += shx(part, 16, lane_); part += shx(part, 32, lane_);
;                 if (fq == 0) ssq_next[(size_t)r * 16 + pn * 4 + wc] = part;
;             }
;         }
.LBB0_554:
	s_andn2_b64 vcc, exec, s[34:35]
	s_cbranch_vccnz .LBB0_556
	v_pk_add_f32 v[80:81], v[72:73], v[136:137]
	v_pk_add_f32 v[76:77], v[68:69], v[132:133]
	global_store_dwordx4 v[88:89], v[78:81], off offset:512 nt
	global_store_dwordx4 v[88:89], v[74:77], off offset:576 nt
.LBB0_556:
	v_add_u32_e32 v134, 0xa0, v210
	v_ashrrev_i32_e32 v135, 31, v134
	s_waitcnt lgkmcnt(0)
	v_lshlrev_b64 v[66:67], 10, v[134:135]
	v_lshl_add_u64 v[136:137], v[66:67], 0, v[208:209]
	v_add_u32_e32 v130, 0xb0, v210
	v_lshl_add_u64 v[66:67], v[136:137], 2, s[14:15]
	v_ashrrev_i32_e32 v131, 31, v130
	global_load_dwordx4 v[94:97], v[66:67], off nt
	global_load_dwordx4 v[90:93], v[66:67], off offset:64 nt
	global_load_dwordx4 v[86:89], v[66:67], off offset:512 nt
	global_load_dwordx4 v[82:85], v[66:67], off offset:576 nt
	v_lshlrev_b64 v[66:67], 10, v[130:131]
	v_lshl_add_u64 v[132:133], v[66:67], 0, v[208:209]
	v_lshl_add_u64 v[66:67], v[132:133], 2, s[14:15]
	global_load_dwordx4 v[78:81], v[66:67], off nt
	global_load_dwordx4 v[74:77], v[66:67], off offset:64 nt
	global_load_dwordx4 v[70:73], v[66:67], off offset:512 nt
	s_nop 0
	global_load_dwordx4 v[66:69], v[66:67], off offset:576 nt
	s_waitcnt vmcnt(0)
	v_pk_add_f32 v[128:129], v[64:65], v[128:129]
	v_pk_add_f32 v[126:127], v[62:63], v[126:127]
	v_pk_add_f32 v[124:125], v[60:61], v[124:125]
	v_pk_add_f32 v[122:123], v[58:59], v[122:123]
	v_lshl_add_u64 v[138:139], v[168:169], 2, s[48:49]
	s_mov_b64 s[34:35], -1
	s_and_b64 vcc, exec, s[6:7]
	v_pk_add_f32 v[62:63], v[54:55], v[118:119]
	v_pk_add_f32 v[58:59], v[50:51], v[114:115]
	global_store_dwordx4 v[138:139], v[126:129], off nt
	global_store_dwordx4 v[138:139], v[122:125], off offset:64 nt
	s_cbranch_vccnz .LBB0_560
	v_cvt_pk_bf16_f32 v50, v126, v127
	v_cvt_pk_bf16_f32 v51, v128, v129
	v_lshl_add_u64 v[54:55], v[168:169], 1, s[12:13]
	flat_store_dwordx2 v[54:55], v[50:51]
	v_cvt_pk_bf16_f32 v50, v122, v123
	v_cvt_pk_bf16_f32 v51, v124, v125
	flat_store_dwordx2 v[54:55], v[50:51] offset:32
	v_mul_f32_e32 v50, v127, v127
	v_mul_f32_e32 v51, v129, v129
	v_fmac_f32_e32 v50, v126, v126
	v_fmac_f32_e32 v51, v128, v128
	v_add_f32_e32 v50, v50, v51
	v_mul_f32_e32 v51, v123, v123
	v_pk_add_f32 v[64:65], v[56:57], v[120:121]
	v_fmac_f32_e32 v51, v122, v122
	v_mul_f32_e32 v114, v63, v63
	v_mul_f32_e32 v115, v65, v65
	v_add_f32_e32 v50, v50, v51
	v_mul_f32_e32 v51, v125, v125
	v_fmac_f32_e32 v114, v62, v62
	v_fmac_f32_e32 v115, v64, v64
	v_fmac_f32_e32 v51, v124, v124
	v_pk_add_f32 v[60:61], v[52:53], v[116:117]
	v_add_f32_e32 v114, v114, v115
	v_mul_f32_e32 v115, v59, v59
	v_add_f32_e32 v50, v51, v50
	v_mul_f32_e32 v51, v61, v61
	v_fmac_f32_e32 v115, v58, v58
	v_fmac_f32_e32 v51, v60, v60
	v_add_f32_e32 v114, v114, v115
	v_add_f32_e32 v51, v51, v114
	v_add_f32_e32 v50, v50, v51
	ds_bpermute_b32 v51, v238, v50
	global_store_dwordx4 v[138:139], v[62:65], off offset:512 nt
	global_store_dwordx4 v[138:139], v[58:61], off offset:576 nt
	v_cvt_pk_bf16_f32 v114, v62, v63
	v_cvt_pk_bf16_f32 v115, v64, v65
	v_cvt_pk_bf16_f32 v64, v58, v59
	s_waitcnt lgkmcnt(0)
	v_add_f32_e32 v50, v50, v51
	ds_bpermute_b32 v51, v237, v50
	v_cvt_pk_bf16_f32 v65, v60, v61
	flat_store_dwordx2 v[54:55], v[114:115] offset:256
	flat_store_dwordx2 v[54:55], v[64:65] offset:288
	s_and_saveexec_b64 s[34:35], s[4:5]
	s_cbranch_execz .LBB0_559
	v_lshlrev_b64 v[54:55], 6, v[166:167]
	v_lshl_add_u64 v[54:55], s[10:11], 0, v[54:55]
	v_lshl_add_u64 v[54:55], s[30:31], 2, v[54:55]
	s_lshl_b32 s92, s62, 2
	v_lshl_add_u64 v[54:55], v[54:55], 0, s[92:93]
	s_waitcnt lgkmcnt(0)
	v_add_f32_e32 v50, v50, v51
	flat_store_dword v[54:55], v50

; DI unsigned pk2(float lo, float hi) { f32x2 v = {lo, hi}; return __builtin_bit_cast(unsigned, __builtin_convertvector(v, bf2_t)); }
; DI float shx(float v, int m, int lane) { return __int_as_float(__builtin_amdgcn_ds_bpermute((lane ^ m) << 2, __float_as_int(v))); }
;     template <int B> DI void proc(const f32x4 (&acc)[2][2][4][2], const f32x4 (&xv)[2][4], int row0, int col0, int pn, int wc, int fq, int lane_) const {
;     ...
;             for (int bj = 0; bj < 2; ++bj) {
;                 const size_t off = (size_t)r * DM + col0 + bj * 128;
;                 const f32x4 v0 = acc[ai][bj][m][0] + xv[q][bj * 2], v1 = acc[ai][bj][m][1] + xv[q][bj * 2 + 1];
;                 *(f32x4*)(xout + off) = v0; *(f32x4*)(xout + off + 16) = v1;
;                 if (XB) {
;                     *(u32x2*)(XB + off) = (u32x2){pk2(v0[0], v0[1]), pk2(v0[2], v0[3])};
;                     *(u32x2*)(XB + off + 16) = (u32x2){pk2(v1[0], v1[1]), pk2(v1[2], v1[3])};
;                     part += (v0[0] * v0[0] + v0[1] * v0[1]) + (v0[2] * v0[2] + v0[3] * v0[3]) + (v1[0] * v1[0] + v1[1] * v1[1]) + (v1[2] * v1[2] + v1[3] * v1[3]);
;                 }
;             }
;             if (XB) {
;                 part += shx(part, 16, lane_); part += shx(part, 32, lane_);
;                 if (fq == 0) ssq_next[(size_t)r * 16 + pn * 4 + wc] = part;
;             }
;         }
.LBB0_560:
	s_andn2_b64 vcc, exec, s[34:35]
	s_cbranch_vccnz .LBB0_562
	v_pk_add_f32 v[64:65], v[56:57], v[120:121]
	v_pk_add_f32 v[60:61], v[52:53], v[116:117]
	global_store_dwordx4 v[138:139], v[62:65], off offset:512 nt
	global_store_dwordx4 v[138:139], v[58:61], off offset:576 nt
.LBB0_562:
	s_waitcnt lgkmcnt(0)
	v_pk_add_f32 v[50:51], v[48:49], v[112:113]
	v_pk_add_f32 v[48:49], v[46:47], v[110:111]
	v_pk_add_f32 v[54:55], v[44:45], v[108:109]
	v_pk_add_f32 v[52:53], v[42:43], v[106:107]
	v_lshl_add_u64 v[56:57], v[164:165], 2, s[48:49]
	s_mov_b64 s[34:35], -1
	s_and_b64 vcc, exec, s[6:7]
	v_pk_add_f32 v[46:47], v[38:39], v[102:103]
	v_pk_add_f32 v[42:43], v[34:35], v[98:99]
	global_store_dwordx4 v[56:57], v[48:51], off nt
	global_store_dwordx4 v[56:57], v[52:55], off offset:64 nt
	s_cbranch_vccnz .LBB0_566
	v_cvt_pk_bf16_f32 v34, v48, v49
	v_cvt_pk_bf16_f32 v35, v50, v51
	v_lshl_add_u64 v[38:39], v[164:165], 1, s[12:13]
	flat_store_dwordx2 v[38:39], v[34:35]
	v_cvt_pk_bf16_f32 v34, v52, v53
	v_cvt_pk_bf16_f32 v35, v54, v55
	flat_store_dwordx2 v[38:39], v[34:35] offset:32
	v_mul_f32_e32 v34, v49, v49
	v_mul_f32_e32 v35, v51, v51
	v_fmac_f32_e32 v34, v48, v48
	v_fmac_f32_e32 v35, v50, v50
	v_add_f32_e32 v34, v34, v35
	v_mul_f32_e32 v35, v53, v53
	v_pk_add_f32 v[48:49], v[40:41], v[104:105]
	v_fmac_f32_e32 v35, v52, v52
	v_mul_f32_e32 v50, v47, v47
	v_mul_f32_e32 v51, v49, v49
	v_add_f32_e32 v34, v34, v35
	v_mul_f32_e32 v35, v55, v55
	v_fmac_f32_e32 v50, v46, v46
	v_fmac_f32_e32 v51, v48, v48
	v_fmac_f32_e32 v35, v54, v54
	v_pk_add_f32 v[44:45], v[36:37], v[100:101]
	v_add_f32_e32 v50, v50, v51
	v_mul_f32_e32 v51, v43, v43
	v_add_f32_e32 v34, v35, v34
	v_mul_f32_e32 v35, v45, v45
	v_fmac_f32_e32 v51, v42, v42
	v_fmac_f32_e32 v35, v44, v44
	v_add_f32_e32 v50, v50, v51
	v_add_f32_e32 v35, v35, v50
	v_add_f32_e32 v34, v34, v35
	ds_bpermute_b32 v35, v238, v34
	global_store_dwordx4 v[56:57], v[46:49], off offset:512 nt
	global_store_dwordx4 v[56:57], v[42:45], off offset:576 nt
	v_cvt_pk_bf16_f32 v50, v46, v47
	v_cvt_pk_bf16_f32 v51, v48, v49
	v_cvt_pk_bf16_f32 v48, v42, v43
	s_waitcnt lgkmcnt(0)
	v_add_f32_e32 v34, v34, v35
	ds_bpermute_b32 v35, v237, v34
	v_cvt_pk_bf16_f32 v49, v44, v45
	flat_store_dwordx2 v[38:39], v[50:51] offset:256
	flat_store_dwordx2 v[38:39], v[48:49] offset:288
	s_and_saveexec_b64 s[34:35], s[4:5]
	s_cbranch_execz .LBB0_565
	v_lshlrev_b64 v[38:39], 6, v[162:163]
	v_lshl_add_u64 v[38:39], s[10:11], 0, v[38:39]
	v_lshl_add_u64 v[38:39], s[30:31], 2, v[38:39]
	s_lshl_b32 s92, s62, 2
	v_lshl_add_u64 v[38:39], v[38:39], 0, s[92:93]
	s_waitcnt lgkmcnt(0)
	v_add_f32_e32 v34, v34, v35
	flat_store_dword v[38:39], v34

; DI unsigned pk2(float lo, float hi) { f32x2 v = {lo, hi}; return __builtin_bit_cast(unsigned, __builtin_convertvector(v, bf2_t)); }
; DI float shx(float v, int m, int lane) { return __int_as_float(__builtin_amdgcn_ds_bpermute((lane ^ m) << 2, __float_as_int(v))); }
;     template <int B> DI void proc(const f32x4 (&acc)[2][2][4][2], const f32x4 (&xv)[2][4], int row0, int col0, int pn, int wc, int fq, int lane_) const {
;     ...
;             for (int bj = 0; bj < 2; ++bj) {
;                 const size_t off = (size_t)r * DM + col0 + bj * 128;
;                 const f32x4 v0 = acc[ai][bj][m][0] + xv[q][bj * 2], v1 = acc[ai][bj][m][1] + xv[q][bj * 2 + 1];
;                 *(f32x4*)(xout + off) = v0; *(f32x4*)(xout + off + 16) = v1;
;                 if (XB) {
;                     *(u32x2*)(XB + off) = (u32x2){pk2(v0[0], v0[1]), pk2(v0[2], v0[3])};
;                     *(u32x2*)(XB + off + 16) = (u32x2){pk2(v1[0], v1[1]), pk2(v1[2], v1[3])};
;                     part += (v0[0] * v0[0] + v0[1] * v0[1]) + (v0[2] * v0[2] + v0[3] * v0[3]) + (v1[0] * v1[0] + v1[1] * v1[1]) + (v1[2] * v1[2] + v1[3] * v1[3]);
;                 }
;             }
;             if (XB) {
;                 part += shx(part, 16, lane_); part += shx(part, 32, lane_);
;                 if (fq == 0) ssq_next[(size_t)r * 16 + pn * 4 + wc] = part;
;             }
;         }
.LBB0_566:
	s_andn2_b64 vcc, exec, s[34:35]
	s_cbranch_vccnz .LBB0_568
	v_pk_add_f32 v[48:49], v[40:41], v[104:105]
	v_pk_add_f32 v[44:45], v[36:37], v[100:101]
	global_store_dwordx4 v[56:57], v[46:49], off offset:512 nt
	global_store_dwordx4 v[56:57], v[42:45], off offset:576 nt
.LBB0_568:
	s_waitcnt lgkmcnt(0)
	v_pk_add_f32 v[34:35], v[32:33], v[96:97]
	v_pk_add_f32 v[32:33], v[30:31], v[94:95]
	v_pk_add_f32 v[38:39], v[28:29], v[92:93]
	v_pk_add_f32 v[36:37], v[26:27], v[90:91]
	v_lshl_add_u64 v[40:41], v[136:137], 2, s[48:49]
	s_mov_b64 s[34:35], -1
	s_and_b64 vcc, exec, s[6:7]
	v_pk_add_f32 v[30:31], v[22:23], v[86:87]
	v_pk_add_f32 v[26:27], v[18:19], v[82:83]
	global_store_dwordx4 v[40:41], v[32:35], off nt
	global_store_dwordx4 v[40:41], v[36:39], off offset:64 nt
	s_cbranch_vccnz .LBB0_572
	v_cvt_pk_bf16_f32 v18, v32, v33
	v_cvt_pk_bf16_f32 v19, v34, v35
	v_lshl_add_u64 v[22:23], v[136:137], 1, s[12:13]
	flat_store_dwordx2 v[22:23], v[18:19]
	v_cvt_pk_bf16_f32 v18, v36, v37
	v_cvt_pk_bf16_f32 v19, v38, v39
	flat_store_dwordx2 v[22:23], v[18:19] offset:32
	v_mul_f32_e32 v18, v33, v33
	v_mul_f32_e32 v19, v35, v35
	v_fmac_f32_e32 v18, v32, v32
	v_fmac_f32_e32 v19, v34, v34
	v_add_f32_e32 v18, v18, v19
	v_mul_f32_e32 v19, v37, v37
	v_pk_add_f32 v[32:33], v[24:25], v[88:89]
	v_fmac_f32_e32 v19, v36, v36
	v_mul_f32_e32 v34, v31, v31
	v_mul_f32_e32 v35, v33, v33
	v_add_f32_e32 v18, v18, v19
	v_mul_f32_e32 v19, v39, v39
	v_fmac_f32_e32 v34, v30, v30
	v_fmac_f32_e32 v35, v32, v32
	v_fmac_f32_e32 v19, v38, v38
	v_pk_add_f32 v[28:29], v[20:21], v[84:85]
	v_add_f32_e32 v34, v34, v35
	v_mul_f32_e32 v35, v27, v27
	v_add_f32_e32 v18, v19, v18
	v_mul_f32_e32 v19, v29, v29
	v_fmac_f32_e32 v35, v26, v26
	v_fmac_f32_e32 v19, v28, v28
	v_add_f32_e32 v34, v34, v35
	v_add_f32_e32 v19, v19, v34
	v_add_f32_e32 v18, v18, v19
	ds_bpermute_b32 v19, v238, v18
	global_store_dwordx4 v[40:41], v[30:33], off offset:512 nt
	global_store_dwordx4 v[40:41], v[26:29], off offset:576 nt
	v_cvt_pk_bf16_f32 v34, v30, v31
	v_cvt_pk_bf16_f32 v35, v32, v33
	v_cvt_pk_bf16_f32 v32, v26, v27
	s_waitcnt lgkmcnt(0)
	v_add_f32_e32 v18, v18, v19
	ds_bpermute_b32 v19, v237, v18
	v_cvt_pk_bf16_f32 v33, v28, v29
	flat_store_dwordx2 v[22:23], v[34:35] offset:256
	flat_store_dwordx2 v[22:23], v[32:33] offset:288
	s_and_saveexec_b64 s[34:35], s[4:5]
	s_cbranch_execz .LBB0_571
	v_lshlrev_b64 v[22:23], 6, v[134:135]
	v_lshl_add_u64 v[22:23], s[10:11], 0, v[22:23]
	v_lshl_add_u64 v[22:23], s[30:31], 2, v[22:23]
	s_lshl_b32 s92, s62, 2
	v_lshl_add_u64 v[22:23], v[22:23], 0, s[92:93]
	s_waitcnt lgkmcnt(0)
	v_add_f32_e32 v18, v18, v19
	flat_store_dword v[22:23], v18

; DI unsigned pk2(float lo, float hi) { f32x2 v = {lo, hi}; return __builtin_bit_cast(unsigned, __builtin_convertvector(v, bf2_t)); }
;     template <int B> DI void proc(const f32x4 (&acc)[2][2][4][2], const f32x4 (&xv)[2][4], int row0, int col0, int pn, int wc, int fq, int lane_) const {
;     ...
;             for (int bj = 0; bj < 2; ++bj) {
;                 const size_t off = (size_t)r * DM + col0 + bj * 128;
;                 const f32x4 v0 = acc[ai][bj][m][0] + xv[q][bj * 2], v1 = acc[ai][bj][m][1] + xv[q][bj * 2 + 1];
;                 *(f32x4*)(xout + off) = v0; *(f32x4*)(xout + off + 16) = v1;
;                 if (XB) {
;                     *(u32x2*)(XB + off) = (u32x2){pk2(v0[0], v0[1]), pk2(v0[2], v0[3])};
;                     *(u32x2*)(XB + off + 16) = (u32x2){pk2(v1[0], v1[1]), pk2(v1[2], v1[3])};
.LBB0_572:
	s_andn2_b64 vcc, exec, s[34:35]
	s_cbranch_vccnz .LBB0_574
	v_pk_add_f32 v[32:33], v[24:25], v[88:89]
	v_pk_add_f32 v[28:29], v[20:21], v[84:85]
	global_store_dwordx4 v[40:41], v[30:33], off offset:512 nt
	global_store_dwordx4 v[40:41], v[26:29], off offset:576 nt
.LBB0_574:
	s_waitcnt lgkmcnt(0)
	v_pk_add_f32 v[18:19], v[16:17], v[80:81]
	v_pk_add_f32 v[16:17], v[14:15], v[78:79]
	v_pk_add_f32 v[22:23], v[12:13], v[76:77]
	v_pk_add_f32 v[20:21], v[10:11], v[74:75]
	v_lshl_add_u64 v[24:25], v[132:133], 2, s[48:49]
	s_mov_b64 s[34:35], -1
	s_and_b64 vcc, exec, s[6:7]
	v_pk_add_f32 v[14:15], v[6:7], v[70:71]
	v_pk_add_f32 v[10:11], v[2:3], v[66:67]
	global_store_dwordx4 v[24:25], v[16:19], off nt
	global_store_dwordx4 v[24:25], v[20:23], off offset:64 nt
	s_cbranch_vccz .LBB0_581
	s_andn2_b64 vcc, exec, s[34:35]
	s_cbranch_vccz .LBB0_584

; DI unsigned pk2(float lo, float hi) { f32x2 v = {lo, hi}; return __builtin_bit_cast(unsigned, __builtin_convertvector(v, bf2_t)); }
; DI float shx(float v, int m, int lane) { return __int_as_float(__builtin_amdgcn_ds_bpermute((lane ^ m) << 2, __float_as_int(v))); }
;     template <int B> DI void proc(const f32x4 (&acc)[2][2][4][2], const f32x4 (&xv)[2][4], int row0, int col0, int pn, int wc, int fq, int lane_) const {
;     ...
;                 if (XB) {
;                     *(u32x2*)(XB + off) = (u32x2){pk2(v0[0], v0[1]), pk2(v0[2], v0[3])};
;                     *(u32x2*)(XB + off + 16) = (u32x2){pk2(v1[0], v1[1]), pk2(v1[2], v1[3])};
;                     part += (v0[0] * v0[0] + v0[1] * v0[1]) + (v0[2] * v0[2] + v0[3] * v0[3]) + (v1[0] * v1[0] + v1[1] * v1[1]) + (v1[2] * v1[2] + v1[3] * v1[3]);
;                 }
;             }
;             if (XB) {
;                 part += shx(part, 16, lane_); part += shx(part, 32, lane_);
;                 if (fq == 0) ssq_next[(size_t)r * 16 + pn * 4 + wc] = part;
;             }
;         }
.LBB0_581:
	v_cvt_pk_bf16_f32 v2, v16, v17
	v_cvt_pk_bf16_f32 v3, v18, v19
	v_lshl_add_u64 v[6:7], v[132:133], 1, s[12:13]
	flat_store_dwordx2 v[6:7], v[2:3]
	v_cvt_pk_bf16_f32 v2, v20, v21
	v_cvt_pk_bf16_f32 v3, v22, v23
	flat_store_dwordx2 v[6:7], v[2:3] offset:32
	v_mul_f32_e32 v2, v17, v17
	v_mul_f32_e32 v3, v19, v19
	v_fmac_f32_e32 v2, v16, v16
	v_fmac_f32_e32 v3, v18, v18
	v_add_f32_e32 v2, v2, v3
	v_mul_f32_e32 v3, v21, v21
	v_pk_add_f32 v[16:17], v[8:9], v[72:73]
	v_fmac_f32_e32 v3, v20, v20
	v_mul_f32_e32 v18, v15, v15
	v_mul_f32_e32 v19, v17, v17
	v_add_f32_e32 v2, v2, v3
	v_mul_f32_e32 v3, v23, v23
	v_fmac_f32_e32 v18, v14, v14
	v_fmac_f32_e32 v19, v16, v16
	v_fmac_f32_e32 v3, v22, v22
	v_pk_add_f32 v[12:13], v[4:5], v[68:69]
	v_add_f32_e32 v18, v18, v19
	v_mul_f32_e32 v19, v11, v11
	v_add_f32_e32 v2, v3, v2
	v_mul_f32_e32 v3, v13, v13
	v_fmac_f32_e32 v19, v10, v10
	v_fmac_f32_e32 v3, v12, v12
	v_add_f32_e32 v18, v18, v19
	v_add_f32_e32 v3, v3, v18
	v_add_f32_e32 v2, v2, v3
	ds_bpermute_b32 v3, v238, v2
	global_store_dwordx4 v[24:25], v[14:17], off offset:512 nt
	global_store_dwordx4 v[24:25], v[10:13], off offset:576 nt
	v_cvt_pk_bf16_f32 v18, v14, v15
	v_cvt_pk_bf16_f32 v19, v16, v17
	v_cvt_pk_bf16_f32 v16, v10, v11
	s_waitcnt lgkmcnt(0)
	v_add_f32_e32 v2, v2, v3
	ds_bpermute_b32 v3, v237, v2
	v_cvt_pk_bf16_f32 v17, v12, v13
	flat_store_dwordx2 v[6:7], v[18:19] offset:256
	flat_store_dwordx2 v[6:7], v[16:17] offset:288
	s_and_saveexec_b64 s[6:7], s[4:5]
	s_cbranch_execz .LBB0_583
	v_lshlrev_b64 v[6:7], 6, v[130:131]
	v_lshl_add_u64 v[6:7], s[10:11], 0, v[6:7]
	v_lshl_add_u64 v[6:7], s[30:31], 2, v[6:7]
	s_lshl_b32 s92, s62, 2
	v_lshl_add_u64 v[6:7], v[6:7], 0, s[92:93]
	s_waitcnt lgkmcnt(0)
	v_add_f32_e32 v2, v2, v3
	flat_store_dword v[6:7], v2

; #define LAS __attribute__((address_space(3)))
; DI unsigned pk2(float lo, float hi) { f32x2 v = {lo, hi}; return __builtin_bit_cast(unsigned, __builtin_convertvector(v, bf2_t)); }
; DI int fresh_lane() { int l; asm volatile("v_mbcnt_lo_u32_b32 %0, -1, 0\n\tv_mbcnt_hi_u32_b32 %0, -1, %0" : "=v"(l)); return l; }
; #define PG8_WAIT_V(n) asm volatile("s_waitcnt vmcnt(" #n ")" ::: "memory")
; #define PG8_BAR __builtin_amdgcn_s_barrier()
; template <class Epi, bool PERM = true, bool DBLK = false>
; __device__ __forceinline__ void gemm_phase(LAS unsigned char* lds, const Gemm g, const StaticOrder& S, const Epi& E, const int tid) {
;     ...
;     PG8_WAIT_V(0);
;     PG8_BAR;
;     if constexpr (Epi::AFTER_DRAIN) E.fused(acc, cur, wr, wc, lds);
;     DI void fused(const f32x4 (&acc)[2][2][4][2], const pg8::Unit& u, int wr, int wc, LAS unsigned char* lds) const {
;         const int lane_ = fresh_lane(), fr = lane_ & 15, fq = lane_ >> 4;
;         const int w8 = wr * 4 + wc;
; #pragma unroll
;         for (int ai = 0; ai < 2; ++ai) {
; #pragma unroll
;             for (int m = 0; m < 4; ++m)
; #pragma unroll
;                 for (int bj = 0; bj < 2; ++bj)
; #pragma unroll
;                     for (int n = 0; n < 2; ++n)
;                         *(LAS f32x4*)(lds + (size_t)(wr * 64 + m * 16 + fr) * 1040 + (bj * 128 + wc * 32 + n * 16 + 4 * fq) * 4) = acc[ai][bj][m][n];
;             __syncthreads();
;             const size_t g0 = (size_t)(u.pm * 256 + ai * 128 + w8 * 16) * DM + u.pn * 256 + lane_ * 4;
;             f32x4 xo[16];
; #pragma unroll
;             for (int rr = 0; rr < 16; ++rr) xo[rr] = *(const f32x4*)(xin + g0 + (size_t)rr * DM);
; #pragma unroll
;             for (int rr = 0; rr < 16; ++rr) {
;                 const f32x4 a = *(const LAS f32x4*)(lds + (size_t)(w8 * 16 + rr) * 1040 + lane_ * 16);
;                 const f32x4 v = a + xo[rr];
;                 *(f32x4*)(xout + g0 + (size_t)rr * DM) = v;
;                 if (XB) {
;                     *(u32x2*)(XB + g0 + (size_t)rr * DM) = (u32x2){pk2(v[0], v[1]), pk2(v[2], v[3])};
;                     float part = (v[0] * v[0] + v[1] * v[1]) + (v[2] * v[2] + v[3] * v[3]);
;                     part = wave_sum(part, lane_);
;                     if (lane_ < 4) ssq_next[(size_t)(u.pm * 256 + ai * 128 + w8 * 16 + rr) * 16 + u.pn * 4 + lane_] = (lane_ == 0) ? part : 0.f;
.LBB0_584:
	v_pk_add_f32 v[16:17], v[8:9], v[72:73]
	v_pk_add_f32 v[12:13], v[4:5], v[68:69]
	global_store_dwordx4 v[24:25], v[14:17], off offset:512 nt
	global_store_dwordx4 v[24:25], v[10:13], off offset:576 nt
	s_andn2_b64 vcc, exec, s[96:97]
	s_cbranch_vccz .LBB0_577
	s_branch .LBB0_578
.LBB0_585:
	s_lshl_b32 s0, s62, 7
	s_waitcnt vmcnt(0)
	s_barrier
	v_mbcnt_lo_u32_b32 v130, -1, 0
	v_mbcnt_hi_u32_b32 v130, -1, v130
	s_add_i32 s0, s0, 0
	v_and_b32_e32 v131, -16, v130
	s_lshl_b32 s1, s62, 4
	v_add_u32_e32 v131, s0, v131
	s_lshl_b32 s0, s74, 8
	s_or_b32 s2, s1, s59
	s_add_i32 s18, s0, s2
	s_lshl_b32 s0, s73, 8
	v_lshlrev_b32_e32 v132, 2, v130
	s_ashr_i32 s1, s0, 31
	v_ashrrev_i32_e32 v133, 31, v132
	v_and_or_b32 v0, v130, 15, s59
	v_lshl_add_u64 v[132:133], v[132:133], 0, s[0:1]
	s_movk_i32 s0, 0x410
	s_ashr_i32 s19, s18, 31
	v_mul_lo_u32 v0, v0, s0
	s_lshl_b64 s[0:1], s[18:19], 10
	v_lshl_add_u64 v[140:141], v[132:133], 0, s[0:1]
	v_add_u32_e32 v138, v131, v0
	v_lshlrev_b64 v[142:143], 2, v[140:141]
	ds_write_b128 v138, v[126:129]
	ds_write_b128 v138, v[122:125] offset:64
	ds_write_b128 v138, v[118:121] offset:512
	ds_write_b128 v138, v[114:117] offset:576
	ds_write_b128 v138, v[110:113] offset:16640
	ds_write_b128 v138, v[106:109] offset:16704
	ds_write_b128 v138, v[102:105] offset:17152
	ds_write_b128 v138, v[98:101] offset:17216
	ds_write_b128 v138, v[94:97] offset:33280
	ds_write_b128 v138, v[90:93] offset:33344
	ds_write_b128 v138, v[86:89] offset:33792
	ds_write_b128 v138, v[82:85] offset:33856
	ds_write_b128 v138, v[78:81] offset:49920
	ds_write_b128 v138, v[74:77] offset:49984
	ds_write_b128 v138, v[70:73] offset:50432
	ds_write_b128 v138, v[66:69] offset:50496
	v_lshl_add_u64 v[66:67], s[14:15], 0, v[142:143]
	s_movk_i32 s80, 0x2000
	v_add_co_u32_e32 v68, vcc, s80, v66
	s_movk_i32 s81, 0x4000
	s_nop 0
	v_addc_co_u32_e32 v69, vcc, 0, v67, vcc
	s_waitcnt vmcnt(0) lgkmcnt(0)
	s_barrier
	global_load_dwordx4 v[126:129], v[66:67], off nt
	global_load_dwordx4 v[122:125], v[68:69], off offset:-4096 nt
	global_load_dwordx4 v[118:121], v[68:69], off nt
	v_add_co_u32_e32 v68, vcc, s81, v66
	s_movk_i32 s0, 0x6000
	s_nop 0
	v_addc_co_u32_e32 v69, vcc, 0, v67, vcc
	global_load_dwordx4 v[114:117], v[68:69], off offset:-4096 nt
	global_load_dwordx4 v[110:113], v[68:69], off nt
	v_add_co_u32_e32 v68, vcc, s0, v66
	s_mov_b32 s0, 0x8000
	s_nop 0
	v_addc_co_u32_e32 v69, vcc, 0, v67, vcc
	global_load_dwordx4 v[106:109], v[68:69], off offset:-4096 nt
	global_load_dwordx4 v[102:105], v[68:69], off nt
	v_add_co_u32_e32 v68, vcc, s0, v66
	s_mov_b32 s0, 0xa000
	s_nop 0
	v_addc_co_u32_e32 v69, vcc, 0, v67, vcc
	global_load_dwordx4 v[98:101], v[68:69], off offset:-4096 nt
	global_load_dwordx4 v[94:97], v[68:69], off nt
	v_add_co_u32_e32 v68, vcc, s0, v66
	s_mov_b32 s0, 0xc000
	s_nop 0
	v_addc_co_u32_e32 v69, vcc, 0, v67, vcc
	global_load_dwordx4 v[90:93], v[68:69], off offset:-4096 nt
	global_load_dwordx4 v[86:89], v[68:69], off nt
	v_add_co_u32_e32 v68, vcc, s0, v66
	s_mov_b32 s0, 0xe000
	s_nop 0
	v_addc_co_u32_e32 v69, vcc, 0, v67, vcc
	global_load_dwordx4 v[82:85], v[68:69], off offset:-4096 nt
	global_load_dwordx4 v[78:81], v[68:69], off nt
	v_add_co_u32_e32 v68, vcc, s0, v66
	s_mov_b32 s0, 0xf000
	s_nop 0
	v_addc_co_u32_e32 v69, vcc, 0, v67, vcc
	v_add_co_u32_e32 v66, vcc, s0, v66
	global_load_dwordx4 v[74:77], v[68:69], off offset:-4096 nt
	global_load_dwordx4 v[70:73], v[68:69], off nt
	v_addc_co_u32_e32 v67, vcc, 0, v67, vcc
	global_load_dwordx4 v[66:69], v[66:67], off nt
	v_lshl_add_u32 v0, v130, 4, 0
	s_mulk_i32 s2, 0x410
	v_add_u32_e32 v0, s2, v0
	ds_read_b128 v[134:137], v0
	s_lshl_b32 s16, s73, 2
	s_mov_b32 s86, s60
	v_readlane_b32 s60, v255, 52
	v_cmp_gt_i32_e64 s[4:5], 4, v130
	v_cmp_eq_u32_e64 s[0:1], 0, v130
	s_ashr_i32 s17, s16, 31
	v_ashrrev_i32_e32 v131, 31, v130
	s_andn2_b64 vcc, exec, s[8:9]
	s_mov_b32 s97, s94
	v_readlane_b32 s37, v255, 51
	v_readlane_b32 s61, v255, 53
	s_waitcnt vmcnt(15) lgkmcnt(0)
	v_pk_add_f32 v[126:127], v[126:127], v[134:135]
	v_cndmask_b32_e64 v134, 0, 1, s[8:9]
	v_pk_add_f32 v[128:129], v[128:129], v[136:137]
	v_lshl_add_u64 v[136:137], s[48:49], 0, v[142:143]
	v_cmp_ne_u32_e64 s[6:7], 1, v134
	v_lshl_add_u64 v[134:135], v[140:141], 1, s[12:13]
	global_store_dwordx4 v[136:137], v[126:129], off nt
	s_cbranch_vccnz .LBB0_589
	v_cvt_pk_bf16_f32 v140, v126, v127
	v_mul_f32_e32 v127, v127, v127
	v_fmac_f32_e32 v127, v126, v126
	v_mul_f32_e32 v126, v129, v129
	v_fmac_f32_e32 v126, v128, v128
	v_add_f32_e32 v126, v127, v126
	v_cvt_pk_bf16_f32 v141, v128, v129
	flat_store_dwordx2 v[134:135], v[140:141]
	v_add_f32_dpp v126, v126, v126 row_ror:1 row_mask:0xf bank_mask:0xf bound_ctrl:1
	s_nop 1
	v_add_f32_dpp v126, v126, v126 row_ror:2 row_mask:0xf bank_mask:0xf bound_ctrl:1
	s_nop 1
	v_add_f32_dpp v126, v126, v126 row_ror:4 row_mask:0xf bank_mask:0xf bound_ctrl:1
	s_nop 1
	v_add_f32_dpp v126, v126, v126 row_ror:8 row_mask:0xf bank_mask:0xf bound_ctrl:1
	s_nop 0
	v_readlane_b32 s24, v126, 0
	v_readlane_b32 s2, v126, 16
	v_readlane_b32 s25, v126, 32
	v_readlane_b32 s3, v126, 48
	s_and_saveexec_b64 s[22:23], s[4:5]
	s_cbranch_execz .LBB0_588
	v_mov_b32_e32 v126, s2
	v_mov_b32_e32 v127, s3
	s_lshl_b64 s[2:3], s[18:19], 6
	s_add_u32 s19, s10, s2
	s_addc_u32 s20, s11, s3
	s_lshl_b64 s[2:3], s[16:17], 2
	v_pk_add_f32 v[126:127], s[24:25], v[126:127]
	s_add_u32 s2, s19, s2
	v_add_f32_e32 v126, v126, v127
	s_addc_u32 s3, s20, s3
	v_cndmask_b32_e64 v128, 0, v126, s[0:1]
	v_lshl_add_u64 v[126:127], v[130:131], 2, s[2:3]
	flat_store_dword v[126:127], v128

; #define LAS __attribute__((address_space(3)))
; DI unsigned pk2(float lo, float hi) { f32x2 v = {lo, hi}; return __builtin_bit_cast(unsigned, __builtin_convertvector(v, bf2_t)); }
;     DI void fused(const f32x4 (&acc)[2][2][4][2], const pg8::Unit& u, int wr, int wc, LAS unsigned char* lds) const {
;     ...
;             for (int rr = 0; rr < 16; ++rr) {
;                 const f32x4 a = *(const LAS f32x4*)(lds + (size_t)(w8 * 16 + rr) * 1040 + lane_ * 16);
;                 const f32x4 v = a + xo[rr];
;                 *(f32x4*)(xout + g0 + (size_t)rr * DM) = v;
;                 if (XB) {
;                     *(u32x2*)(XB + g0 + (size_t)rr * DM) = (u32x2){pk2(v[0], v[1]), pk2(v[2], v[3])};
;                     float part = (v[0] * v[0] + v[1] * v[1]) + (v[2] * v[2] + v[3] * v[3]);
;                     part = wave_sum(part, lane_);
;                     if (lane_ < 4) ssq_next[(size_t)(u.pm * 256 + ai * 128 + w8 * 16 + rr) * 16 + u.pn * 4 + lane_] = (lane_ == 0) ? part : 0.f;
;                 }
.LBB0_589:
	ds_read_b128 v[126:129], v0 offset:1040
	s_waitcnt vmcnt(0) lgkmcnt(0)
	v_pk_add_f32 v[122:123], v[122:123], v[126:127]
	v_add_co_u32_e32 v126, vcc, 0x1000, v136
	v_pk_add_f32 v[124:125], v[124:125], v[128:129]
	s_nop 0
	v_addc_co_u32_e32 v127, vcc, 0, v137, vcc
	s_and_b64 vcc, exec, s[6:7]
	global_store_dwordx4 v[126:127], v[122:125], off nt
	s_cbranch_vccnz .LBB0_593
	v_cvt_pk_bf16_f32 v126, v122, v123
	v_mul_f32_e32 v123, v123, v123
	v_fmac_f32_e32 v123, v122, v122
	v_mul_f32_e32 v122, v125, v125
	v_fmac_f32_e32 v122, v124, v124
	v_add_f32_e32 v122, v123, v122
	v_cvt_pk_bf16_f32 v127, v124, v125
	flat_store_dwordx2 v[134:135], v[126:127] offset:2048
	v_add_f32_dpp v122, v122, v122 row_ror:1 row_mask:0xf bank_mask:0xf bound_ctrl:1
	s_nop 1
	v_add_f32_dpp v122, v122, v122 row_ror:2 row_mask:0xf bank_mask:0xf bound_ctrl:1
	s_nop 1
	v_add_f32_dpp v122, v122, v122 row_ror:4 row_mask:0xf bank_mask:0xf bound_ctrl:1
	s_nop 1
	v_add_f32_dpp v122, v122, v122 row_ror:8 row_mask:0xf bank_mask:0xf bound_ctrl:1
	s_nop 0
	v_readlane_b32 s24, v122, 0
	v_readlane_b32 s2, v122, 16
	v_readlane_b32 s25, v122, 32
	v_readlane_b32 s3, v122, 48
	s_and_saveexec_b64 s[22:23], s[4:5]
	s_cbranch_execz .LBB0_592
	v_mov_b32_e32 v122, s2
	s_or_b32 s2, s18, 1
	v_mov_b32_e32 v123, s3
	s_ashr_i32 s3, s2, 31
	s_lshl_b64 s[2:3], s[2:3], 6
	s_add_u32 s19, s10, s2
	s_addc_u32 s20, s11, s3
	s_lshl_b64 s[2:3], s[16:17], 2
	v_pk_add_f32 v[122:123], s[24:25], v[122:123]
	s_add_u32 s2, s19, s2
	v_add_f32_e32 v122, v122, v123
	s_addc_u32 s3, s20, s3
	v_cndmask_b32_e64 v124, 0, v122, s[0:1]
	v_lshl_add_u64 v[122:123], v[130:131], 2, s[2:3]
	flat_store_dword v[122:123], v124

; #define LAS __attribute__((address_space(3)))
; DI unsigned pk2(float lo, float hi) { f32x2 v = {lo, hi}; return __builtin_bit_cast(unsigned, __builtin_convertvector(v, bf2_t)); }
;     DI void fused(const f32x4 (&acc)[2][2][4][2], const pg8::Unit& u, int wr, int wc, LAS unsigned char* lds) const {
;     ...
;             for (int rr = 0; rr < 16; ++rr) {
;                 const f32x4 a = *(const LAS f32x4*)(lds + (size_t)(w8 * 16 + rr) * 1040 + lane_ * 16);
;                 const f32x4 v = a + xo[rr];
;                 *(f32x4*)(xout + g0 + (size_t)rr * DM) = v;
;                 if (XB) {
;                     *(u32x2*)(XB + g0 + (size_t)rr * DM) = (u32x2){pk2(v[0], v[1]), pk2(v[2], v[3])};
;                     float part = (v[0] * v[0] + v[1] * v[1]) + (v[2] * v[2] + v[3] * v[3]);
;                     part = wave_sum(part, lane_);
;                     if (lane_ < 4) ssq_next[(size_t)(u.pm * 256 + ai * 128 + w8 * 16 + rr) * 16 + u.pn * 4 + lane_] = (lane_ == 0) ? part : 0.f;
;                 }
.LBB0_593:
	ds_read_b128 v[122:125], v0 offset:2080
	s_waitcnt lgkmcnt(0)
	v_pk_add_f32 v[118:119], v[118:119], v[122:123]
	v_add_co_u32_e32 v122, vcc, 0x2000, v136
	v_pk_add_f32 v[120:121], v[120:121], v[124:125]
	s_nop 0
	v_addc_co_u32_e32 v123, vcc, 0, v137, vcc
	s_and_b64 vcc, exec, s[6:7]
	global_store_dwordx4 v[122:123], v[118:121], off nt
	s_cbranch_vccnz .LBB0_597
	v_cvt_pk_bf16_f32 v122, v118, v119
	v_mul_f32_e32 v119, v119, v119
	v_fmac_f32_e32 v119, v118, v118
	v_mul_f32_e32 v118, v121, v121
	v_fmac_f32_e32 v118, v120, v120
	v_add_f32_e32 v118, v119, v118
	v_add_co_u32_e32 v124, vcc, 0x1000, v134
	s_nop 0
	v_add_f32_dpp v118, v118, v118 row_ror:1 row_mask:0xf bank_mask:0xf bound_ctrl:1
	v_cvt_pk_bf16_f32 v123, v120, v121
	v_addc_co_u32_e32 v125, vcc, 0, v135, vcc
	v_add_f32_dpp v118, v118, v118 row_ror:2 row_mask:0xf bank_mask:0xf bound_ctrl:1
	flat_store_dwordx2 v[124:125], v[122:123]
	s_nop 0
	v_add_f32_dpp v118, v118, v118 row_ror:4 row_mask:0xf bank_mask:0xf bound_ctrl:1
	s_nop 1
	v_add_f32_dpp v118, v118, v118 row_ror:8 row_mask:0xf bank_mask:0xf bound_ctrl:1
	s_nop 0
	v_readlane_b32 s24, v118, 0
	v_readlane_b32 s2, v118, 16
	v_readlane_b32 s25, v118, 32
	v_readlane_b32 s3, v118, 48
	s_and_saveexec_b64 s[22:23], s[4:5]
	s_cbranch_execz .LBB0_596
	v_mov_b32_e32 v118, s2
	s_or_b32 s2, s18, 2
	v_mov_b32_e32 v119, s3
	s_ashr_i32 s3, s2, 31
	s_lshl_b64 s[2:3], s[2:3], 6
	s_add_u32 s19, s10, s2
	s_addc_u32 s20, s11, s3
	s_lshl_b64 s[2:3], s[16:17], 2
	v_pk_add_f32 v[118:119], s[24:25], v[118:119]
	s_add_u32 s2, s19, s2
	v_add_f32_e32 v118, v118, v119
	s_addc_u32 s3, s20, s3
	v_cndmask_b32_e64 v120, 0, v118, s[0:1]
	v_lshl_add_u64 v[118:119], v[130:131], 2, s[2:3]
	flat_store_dword v[118:119], v120

; #define LAS __attribute__((address_space(3)))
; DI unsigned pk2(float lo, float hi) { f32x2 v = {lo, hi}; return __builtin_bit_cast(unsigned, __builtin_convertvector(v, bf2_t)); }
;     DI void fused(const f32x4 (&acc)[2][2][4][2], const pg8::Unit& u, int wr, int wc, LAS unsigned char* lds) const {
;     ...
;             for (int rr = 0; rr < 16; ++rr) {
;                 const f32x4 a = *(const LAS f32x4*)(lds + (size_t)(w8 * 16 + rr) * 1040 + lane_ * 16);
;                 const f32x4 v = a + xo[rr];
;                 *(f32x4*)(xout + g0 + (size_t)rr * DM) = v;
;                 if (XB) {
;                     *(u32x2*)(XB + g0 + (size_t)rr * DM) = (u32x2){pk2(v[0], v[1]), pk2(v[2], v[3])};
;                     float part = (v[0] * v[0] + v[1] * v[1]) + (v[2] * v[2] + v[3] * v[3]);
;                     part = wave_sum(part, lane_);
;                     if (lane_ < 4) ssq_next[(size_t)(u.pm * 256 + ai * 128 + w8 * 16 + rr) * 16 + u.pn * 4 + lane_] = (lane_ == 0) ? part : 0.f;
;                 }
.LBB0_597:
	ds_read_b128 v[118:121], v0 offset:3120
	s_waitcnt lgkmcnt(0)
	v_pk_add_f32 v[114:115], v[114:115], v[118:119]
	v_add_co_u32_e32 v118, vcc, 0x3000, v136
	v_pk_add_f32 v[116:117], v[116:117], v[120:121]
	s_nop 0
	v_addc_co_u32_e32 v119, vcc, 0, v137, vcc
	s_and_b64 vcc, exec, s[6:7]
	global_store_dwordx4 v[118:119], v[114:117], off nt
	s_cbranch_vccnz .LBB0_601
	v_cvt_pk_bf16_f32 v118, v114, v115
	v_mul_f32_e32 v115, v115, v115
	v_fmac_f32_e32 v115, v114, v114
	v_mul_f32_e32 v114, v117, v117
	v_fmac_f32_e32 v114, v116, v116
	v_add_f32_e32 v114, v115, v114
	v_add_co_u32_e32 v120, vcc, 0x1000, v134
	s_nop 0
	v_add_f32_dpp v114, v114, v114 row_ror:1 row_mask:0xf bank_mask:0xf bound_ctrl:1
	v_cvt_pk_bf16_f32 v119, v116, v117
	v_addc_co_u32_e32 v121, vcc, 0, v135, vcc
	v_add_f32_dpp v114, v114, v114 row_ror:2 row_mask:0xf bank_mask:0xf bound_ctrl:1
	flat_store_dwordx2 v[120:121], v[118:119] offset:2048
	s_nop 0
	v_add_f32_dpp v114, v114, v114 row_ror:4 row_mask:0xf bank_mask:0xf bound_ctrl:1
	s_nop 1
	v_add_f32_dpp v114, v114, v114 row_ror:8 row_mask:0xf bank_mask:0xf bound_ctrl:1
	s_nop 0
	v_readlane_b32 s24, v114, 0
	v_readlane_b32 s2, v114, 16
	v_readlane_b32 s25, v114, 32
	v_readlane_b32 s3, v114, 48
	s_and_saveexec_b64 s[22:23], s[4:5]
	s_cbranch_execz .LBB0_600
	v_mov_b32_e32 v114, s2
	s_or_b32 s2, s18, 3
	v_mov_b32_e32 v115, s3
	s_ashr_i32 s3, s2, 31
	s_lshl_b64 s[2:3], s[2:3], 6
	s_add_u32 s19, s10, s2
	s_addc_u32 s20, s11, s3
	s_lshl_b64 s[2:3], s[16:17], 2
	v_pk_add_f32 v[114:115], s[24:25], v[114:115]
	s_add_u32 s2, s19, s2
	v_add_f32_e32 v114, v114, v115
	s_addc_u32 s3, s20, s3
	v_cndmask_b32_e64 v116, 0, v114, s[0:1]
	v_lshl_add_u64 v[114:115], v[130:131], 2, s[2:3]
	flat_store_dword v[114:115], v116

; #define LAS __attribute__((address_space(3)))
; DI unsigned pk2(float lo, float hi) { f32x2 v = {lo, hi}; return __builtin_bit_cast(unsigned, __builtin_convertvector(v, bf2_t)); }
;     DI void fused(const f32x4 (&acc)[2][2][4][2], const pg8::Unit& u, int wr, int wc, LAS unsigned char* lds) const {
;     ...
;             for (int rr = 0; rr < 16; ++rr) {
;                 const f32x4 a = *(const LAS f32x4*)(lds + (size_t)(w8 * 16 + rr) * 1040 + lane_ * 16);
;                 const f32x4 v = a + xo[rr];
;                 *(f32x4*)(xout + g0 + (size_t)rr * DM) = v;
;                 if (XB) {
;                     *(u32x2*)(XB + g0 + (size_t)rr * DM) = (u32x2){pk2(v[0], v[1]), pk2(v[2], v[3])};
;                     float part = (v[0] * v[0] + v[1] * v[1]) + (v[2] * v[2] + v[3] * v[3]);
;                     part = wave_sum(part, lane_);
;                     if (lane_ < 4) ssq_next[(size_t)(u.pm * 256 + ai * 128 + w8 * 16 + rr) * 16 + u.pn * 4 + lane_] = (lane_ == 0) ? part : 0.f;
;                 }
.LBB0_601:
	ds_read_b128 v[114:117], v0 offset:4160
	s_waitcnt lgkmcnt(0)
	v_pk_add_f32 v[110:111], v[110:111], v[114:115]
	v_add_co_u32_e32 v114, vcc, 0x4000, v136
	v_pk_add_f32 v[112:113], v[112:113], v[116:117]
	s_nop 0
	v_addc_co_u32_e32 v115, vcc, 0, v137, vcc
	s_and_b64 vcc, exec, s[6:7]
	global_store_dwordx4 v[114:115], v[110:113], off nt
	s_cbranch_vccnz .LBB0_605
	v_cvt_pk_bf16_f32 v114, v110, v111
	v_mul_f32_e32 v111, v111, v111
	v_fmac_f32_e32 v111, v110, v110
	v_mul_f32_e32 v110, v113, v113
	v_fmac_f32_e32 v110, v112, v112
	v_add_f32_e32 v110, v111, v110
	v_add_co_u32_e32 v116, vcc, 0x2000, v134
	s_nop 0
	v_add_f32_dpp v110, v110, v110 row_ror:1 row_mask:0xf bank_mask:0xf bound_ctrl:1
	v_cvt_pk_bf16_f32 v115, v112, v113
	v_addc_co_u32_e32 v117, vcc, 0, v135, vcc
	v_add_f32_dpp v110, v110, v110 row_ror:2 row_mask:0xf bank_mask:0xf bound_ctrl:1
	flat_store_dwordx2 v[116:117], v[114:115]
	s_nop 0
	v_add_f32_dpp v110, v110, v110 row_ror:4 row_mask:0xf bank_mask:0xf bound_ctrl:1
	s_nop 1
	v_add_f32_dpp v110, v110, v110 row_ror:8 row_mask:0xf bank_mask:0xf bound_ctrl:1
	s_nop 0
	v_readlane_b32 s24, v110, 0
	v_readlane_b32 s2, v110, 16
	v_readlane_b32 s25, v110, 32
	v_readlane_b32 s3, v110, 48
	s_and_saveexec_b64 s[22:23], s[4:5]
	s_cbranch_execz .LBB0_604
	v_mov_b32_e32 v110, s2
	s_or_b32 s2, s18, 4
	v_mov_b32_e32 v111, s3
	s_ashr_i32 s3, s2, 31
	s_lshl_b64 s[2:3], s[2:3], 6
	s_add_u32 s19, s10, s2
	s_addc_u32 s20, s11, s3
	s_lshl_b64 s[2:3], s[16:17], 2
	v_pk_add_f32 v[110:111], s[24:25], v[110:111]
	s_add_u32 s2, s19, s2
	v_add_f32_e32 v110, v110, v111
	s_addc_u32 s3, s20, s3
	v_cndmask_b32_e64 v112, 0, v110, s[0:1]
	v_lshl_add_u64 v[110:111], v[130:131], 2, s[2:3]
	flat_store_dword v[110:111], v112

; #define LAS __attribute__((address_space(3)))
; DI unsigned pk2(float lo, float hi) { f32x2 v = {lo, hi}; return __builtin_bit_cast(unsigned, __builtin_convertvector(v, bf2_t)); }
;     DI void fused(const f32x4 (&acc)[2][2][4][2], const pg8::Unit& u, int wr, int wc, LAS unsigned char* lds) const {
;     ...
;             for (int rr = 0; rr < 16; ++rr) {
;                 const f32x4 a = *(const LAS f32x4*)(lds + (size_t)(w8 * 16 + rr) * 1040 + lane_ * 16);
;                 const f32x4 v = a + xo[rr];
;                 *(f32x4*)(xout + g0 + (size_t)rr * DM) = v;
;                 if (XB) {
;                     *(u32x2*)(XB + g0 + (size_t)rr * DM) = (u32x2){pk2(v[0], v[1]), pk2(v[2], v[3])};
;                     float part = (v[0] * v[0] + v[1] * v[1]) + (v[2] * v[2] + v[3] * v[3]);
;                     part = wave_sum(part, lane_);
;                     if (lane_ < 4) ssq_next[(size_t)(u.pm * 256 + ai * 128 + w8 * 16 + rr) * 16 + u.pn * 4 + lane_] = (lane_ == 0) ? part : 0.f;
;                 }
.LBB0_605:
	ds_read_b128 v[110:113], v0 offset:5200
	s_waitcnt lgkmcnt(0)
	v_pk_add_f32 v[106:107], v[106:107], v[110:111]
	v_add_co_u32_e32 v110, vcc, 0x5000, v136
	v_pk_add_f32 v[108:109], v[108:109], v[112:113]
	s_nop 0
	v_addc_co_u32_e32 v111, vcc, 0, v137, vcc
	s_and_b64 vcc, exec, s[6:7]
	global_store_dwordx4 v[110:111], v[106:109], off nt
	s_cbranch_vccnz .LBB0_609
	v_cvt_pk_bf16_f32 v110, v106, v107
	v_mul_f32_e32 v107, v107, v107
	v_fmac_f32_e32 v107, v106, v106
	v_mul_f32_e32 v106, v109, v109
	v_fmac_f32_e32 v106, v108, v108
	v_add_f32_e32 v106, v107, v106
	v_add_co_u32_e32 v112, vcc, 0x2000, v134
	s_nop 0
	v_add_f32_dpp v106, v106, v106 row_ror:1 row_mask:0xf bank_mask:0xf bound_ctrl:1
	v_cvt_pk_bf16_f32 v111, v108, v109
	v_addc_co_u32_e32 v113, vcc, 0, v135, vcc
	v_add_f32_dpp v106, v106, v106 row_ror:2 row_mask:0xf bank_mask:0xf bound_ctrl:1
	flat_store_dwordx2 v[112:113], v[110:111] offset:2048
	s_nop 0
	v_add_f32_dpp v106, v106, v106 row_ror:4 row_mask:0xf bank_mask:0xf bound_ctrl:1
	s_nop 1
	v_add_f32_dpp v106, v106, v106 row_ror:8 row_mask:0xf bank_mask:0xf bound_ctrl:1
	s_nop 0
	v_readlane_b32 s24, v106, 0
	v_readlane_b32 s2, v106, 16
	v_readlane_b32 s25, v106, 32
	v_readlane_b32 s3, v106, 48
	s_and_saveexec_b64 s[22:23], s[4:5]
	s_cbranch_execz .LBB0_608
	v_mov_b32_e32 v106, s2
	s_or_b32 s2, s18, 5
	v_mov_b32_e32 v107, s3
	s_ashr_i32 s3, s2, 31
	s_lshl_b64 s[2:3], s[2:3], 6
	s_add_u32 s19, s10, s2
	s_addc_u32 s20, s11, s3
	s_lshl_b64 s[2:3], s[16:17], 2
	v_pk_add_f32 v[106:107], s[24:25], v[106:107]
	s_add_u32 s2, s19, s2
	v_add_f32_e32 v106, v106, v107
	s_addc_u32 s3, s20, s3
	v_cndmask_b32_e64 v108, 0, v106, s[0:1]
	v_lshl_add_u64 v[106:107], v[130:131], 2, s[2:3]
	flat_store_dword v[106:107], v108

; #define LAS __attribute__((address_space(3)))
; DI unsigned pk2(float lo, float hi) { f32x2 v = {lo, hi}; return __builtin_bit_cast(unsigned, __builtin_convertvector(v, bf2_t)); }
;     DI void fused(const f32x4 (&acc)[2][2][4][2], const pg8::Unit& u, int wr, int wc, LAS unsigned char* lds) const {
;     ...
;             for (int rr = 0; rr < 16; ++rr) {
;                 const f32x4 a = *(const LAS f32x4*)(lds + (size_t)(w8 * 16 + rr) * 1040 + lane_ * 16);
;                 const f32x4 v = a + xo[rr];
;                 *(f32x4*)(xout + g0 + (size_t)rr * DM) = v;
;                 if (XB) {
;                     *(u32x2*)(XB + g0 + (size_t)rr * DM) = (u32x2){pk2(v[0], v[1]), pk2(v[2], v[3])};
;                     float part = (v[0] * v[0] + v[1] * v[1]) + (v[2] * v[2] + v[3] * v[3]);
;                     part = wave_sum(part, lane_);
;                     if (lane_ < 4) ssq_next[(size_t)(u.pm * 256 + ai * 128 + w8 * 16 + rr) * 16 + u.pn * 4 + lane_] = (lane_ == 0) ? part : 0.f;
;                 }
.LBB0_609:
	ds_read_b128 v[106:109], v0 offset:6240
	s_waitcnt lgkmcnt(0)
	v_pk_add_f32 v[102:103], v[102:103], v[106:107]
	v_add_co_u32_e32 v106, vcc, 0x6000, v136
	v_pk_add_f32 v[104:105], v[104:105], v[108:109]
	s_nop 0
	v_addc_co_u32_e32 v107, vcc, 0, v137, vcc
	s_and_b64 vcc, exec, s[6:7]
	global_store_dwordx4 v[106:107], v[102:105], off nt
	s_cbranch_vccnz .LBB0_613
	v_cvt_pk_bf16_f32 v106, v102, v103
	v_mul_f32_e32 v103, v103, v103
	v_fmac_f32_e32 v103, v102, v102
	v_mul_f32_e32 v102, v105, v105
	v_fmac_f32_e32 v102, v104, v104
	v_add_f32_e32 v102, v103, v102
	v_add_co_u32_e32 v108, vcc, 0x3000, v134
	s_nop 0
	v_add_f32_dpp v102, v102, v102 row_ror:1 row_mask:0xf bank_mask:0xf bound_ctrl:1
	v_cvt_pk_bf16_f32 v107, v104, v105
	v_addc_co_u32_e32 v109, vcc, 0, v135, vcc
	v_add_f32_dpp v102, v102, v102 row_ror:2 row_mask:0xf bank_mask:0xf bound_ctrl:1
	flat_store_dwordx2 v[108:109], v[106:107]
	s_nop 0
	v_add_f32_dpp v102, v102, v102 row_ror:4 row_mask:0xf bank_mask:0xf bound_ctrl:1
	s_nop 1
	v_add_f32_dpp v102, v102, v102 row_ror:8 row_mask:0xf bank_mask:0xf bound_ctrl:1
	s_nop 0
	v_readlane_b32 s24, v102, 0
	v_readlane_b32 s2, v102, 16
	v_readlane_b32 s25, v102, 32
	v_readlane_b32 s3, v102, 48
	s_and_saveexec_b64 s[22:23], s[4:5]
	s_cbranch_execz .LBB0_612
	v_mov_b32_e32 v102, s2
	s_or_b32 s2, s18, 6
	v_mov_b32_e32 v103, s3
	s_ashr_i32 s3, s2, 31
	s_lshl_b64 s[2:3], s[2:3], 6
	s_add_u32 s19, s10, s2
	s_addc_u32 s20, s11, s3
	s_lshl_b64 s[2:3], s[16:17], 2
	v_pk_add_f32 v[102:103], s[24:25], v[102:103]
	s_add_u32 s2, s19, s2
	v_add_f32_e32 v102, v102, v103
	s_addc_u32 s3, s20, s3
	v_cndmask_b32_e64 v104, 0, v102, s[0:1]
	v_lshl_add_u64 v[102:103], v[130:131], 2, s[2:3]
	flat_store_dword v[102:103], v104

; #define LAS __attribute__((address_space(3)))
; DI unsigned pk2(float lo, float hi) { f32x2 v = {lo, hi}; return __builtin_bit_cast(unsigned, __builtin_convertvector(v, bf2_t)); }
;     DI void fused(const f32x4 (&acc)[2][2][4][2], const pg8::Unit& u, int wr, int wc, LAS unsigned char* lds) const {
;     ...
;             for (int rr = 0; rr < 16; ++rr) {
;                 const f32x4 a = *(const LAS f32x4*)(lds + (size_t)(w8 * 16 + rr) * 1040 + lane_ * 16);
;                 const f32x4 v = a + xo[rr];
;                 *(f32x4*)(xout + g0 + (size_t)rr * DM) = v;
;                 if (XB) {
;                     *(u32x2*)(XB + g0 + (size_t)rr * DM) = (u32x2){pk2(v[0], v[1]), pk2(v[2], v[3])};
;                     float part = (v[0] * v[0] + v[1] * v[1]) + (v[2] * v[2] + v[3] * v[3]);
;                     part = wave_sum(part, lane_);
;                     if (lane_ < 4) ssq_next[(size_t)(u.pm * 256 + ai * 128 + w8 * 16 + rr) * 16 + u.pn * 4 + lane_] = (lane_ == 0) ? part : 0.f;
;                 }
.LBB0_613:
	ds_read_b128 v[102:105], v0 offset:7280
	s_waitcnt lgkmcnt(0)
	v_pk_add_f32 v[98:99], v[98:99], v[102:103]
	v_add_co_u32_e32 v102, vcc, 0x7000, v136
	v_pk_add_f32 v[100:101], v[100:101], v[104:105]
	s_nop 0
	v_addc_co_u32_e32 v103, vcc, 0, v137, vcc
	s_and_b64 vcc, exec, s[6:7]
	global_store_dwordx4 v[102:103], v[98:101], off nt
	s_cbranch_vccnz .LBB0_617
	v_cvt_pk_bf16_f32 v102, v98, v99
	v_mul_f32_e32 v99, v99, v99
	v_fmac_f32_e32 v99, v98, v98
	v_mul_f32_e32 v98, v101, v101
	v_fmac_f32_e32 v98, v100, v100
	v_add_f32_e32 v98, v99, v98
	v_add_co_u32_e32 v104, vcc, 0x3000, v134
	s_nop 0
	v_add_f32_dpp v98, v98, v98 row_ror:1 row_mask:0xf bank_mask:0xf bound_ctrl:1
	v_cvt_pk_bf16_f32 v103, v100, v101
	v_addc_co_u32_e32 v105, vcc, 0, v135, vcc
	v_add_f32_dpp v98, v98, v98 row_ror:2 row_mask:0xf bank_mask:0xf bound_ctrl:1
	flat_store_dwordx2 v[104:105], v[102:103] offset:2048
	s_nop 0
	v_add_f32_dpp v98, v98, v98 row_ror:4 row_mask:0xf bank_mask:0xf bound_ctrl:1
	s_nop 1
	v_add_f32_dpp v98, v98, v98 row_ror:8 row_mask:0xf bank_mask:0xf bound_ctrl:1
	s_nop 0
	v_readlane_b32 s24, v98, 0
	v_readlane_b32 s2, v98, 16
	v_readlane_b32 s25, v98, 32
	v_readlane_b32 s3, v98, 48
	s_and_saveexec_b64 s[22:23], s[4:5]
	s_cbranch_execz .LBB0_616
	v_mov_b32_e32 v98, s2
	s_or_b32 s2, s18, 7
	v_mov_b32_e32 v99, s3
	s_ashr_i32 s3, s2, 31
	s_lshl_b64 s[2:3], s[2:3], 6
	s_add_u32 s19, s10, s2
	s_addc_u32 s20, s11, s3
	s_lshl_b64 s[2:3], s[16:17], 2
	v_pk_add_f32 v[98:99], s[24:25], v[98:99]
	s_add_u32 s2, s19, s2
	v_add_f32_e32 v98, v98, v99
	s_addc_u32 s3, s20, s3
	v_cndmask_b32_e64 v100, 0, v98, s[0:1]
	v_lshl_add_u64 v[98:99], v[130:131], 2, s[2:3]
	flat_store_dword v[98:99], v100

; #define LAS __attribute__((address_space(3)))
; DI unsigned pk2(float lo, float hi) { f32x2 v = {lo, hi}; return __builtin_bit_cast(unsigned, __builtin_convertvector(v, bf2_t)); }
;     DI void fused(const f32x4 (&acc)[2][2][4][2], const pg8::Unit& u, int wr, int wc, LAS unsigned char* lds) const {
;     ...
;             for (int rr = 0; rr < 16; ++rr) {
;                 const f32x4 a = *(const LAS f32x4*)(lds + (size_t)(w8 * 16 + rr) * 1040 + lane_ * 16);
;                 const f32x4 v = a + xo[rr];
;                 *(f32x4*)(xout + g0 + (size_t)rr * DM) = v;
;                 if (XB) {
;                     *(u32x2*)(XB + g0 + (size_t)rr * DM) = (u32x2){pk2(v[0], v[1]), pk2(v[2], v[3])};
;                     float part = (v[0] * v[0] + v[1] * v[1]) + (v[2] * v[2] + v[3] * v[3]);
;                     part = wave_sum(part, lane_);
;                     if (lane_ < 4) ssq_next[(size_t)(u.pm * 256 + ai * 128 + w8 * 16 + rr) * 16 + u.pn * 4 + lane_] = (lane_ == 0) ? part : 0.f;
;                 }
.LBB0_617:
	ds_read_b128 v[98:101], v0 offset:8320
	s_waitcnt lgkmcnt(0)
	v_pk_add_f32 v[94:95], v[94:95], v[98:99]
	v_add_co_u32_e32 v98, vcc, 0x8000, v136
	v_pk_add_f32 v[96:97], v[96:97], v[100:101]
	s_nop 0
	v_addc_co_u32_e32 v99, vcc, 0, v137, vcc
	s_and_b64 vcc, exec, s[6:7]
	global_store_dwordx4 v[98:99], v[94:97], off nt
	s_cbranch_vccnz .LBB0_621
	v_cvt_pk_bf16_f32 v98, v94, v95
	v_mul_f32_e32 v95, v95, v95
	v_fmac_f32_e32 v95, v94, v94
	v_mul_f32_e32 v94, v97, v97
	v_fmac_f32_e32 v94, v96, v96
	v_add_f32_e32 v94, v95, v94
	v_add_co_u32_e32 v100, vcc, 0x4000, v134
	s_nop 0
	v_add_f32_dpp v94, v94, v94 row_ror:1 row_mask:0xf bank_mask:0xf bound_ctrl:1
	v_cvt_pk_bf16_f32 v99, v96, v97
	v_addc_co_u32_e32 v101, vcc, 0, v135, vcc
	v_add_f32_dpp v94, v94, v94 row_ror:2 row_mask:0xf bank_mask:0xf bound_ctrl:1
	flat_store_dwordx2 v[100:101], v[98:99]
	s_nop 0
	v_add_f32_dpp v94, v94, v94 row_ror:4 row_mask:0xf bank_mask:0xf bound_ctrl:1
	s_nop 1
	v_add_f32_dpp v94, v94, v94 row_ror:8 row_mask:0xf bank_mask:0xf bound_ctrl:1
	s_nop 0
	v_readlane_b32 s24, v94, 0
	v_readlane_b32 s2, v94, 16
	v_readlane_b32 s25, v94, 32
	v_readlane_b32 s3, v94, 48
	s_and_saveexec_b64 s[22:23], s[4:5]
	s_cbranch_execz .LBB0_620
	v_mov_b32_e32 v94, s2
	s_or_b32 s2, s18, 8
	v_mov_b32_e32 v95, s3
	s_ashr_i32 s3, s2, 31
	s_lshl_b64 s[2:3], s[2:3], 6
	s_add_u32 s19, s10, s2
	s_addc_u32 s20, s11, s3
	s_lshl_b64 s[2:3], s[16:17], 2
	v_pk_add_f32 v[94:95], s[24:25], v[94:95]
	s_add_u32 s2, s19, s2
	v_add_f32_e32 v94, v94, v95
	s_addc_u32 s3, s20, s3
	v_cndmask_b32_e64 v96, 0, v94, s[0:1]
	v_lshl_add_u64 v[94:95], v[130:131], 2, s[2:3]
	flat_store_dword v[94:95], v96

; #define LAS __attribute__((address_space(3)))
; DI unsigned pk2(float lo, float hi) { f32x2 v = {lo, hi}; return __builtin_bit_cast(unsigned, __builtin_convertvector(v, bf2_t)); }
;     DI void fused(const f32x4 (&acc)[2][2][4][2], const pg8::Unit& u, int wr, int wc, LAS unsigned char* lds) const {
;     ...
;             for (int rr = 0; rr < 16; ++rr) {
;                 const f32x4 a = *(const LAS f32x4*)(lds + (size_t)(w8 * 16 + rr) * 1040 + lane_ * 16);
;                 const f32x4 v = a + xo[rr];
;                 *(f32x4*)(xout + g0 + (size_t)rr * DM) = v;
;                 if (XB) {
;                     *(u32x2*)(XB + g0 + (size_t)rr * DM) = (u32x2){pk2(v[0], v[1]), pk2(v[2], v[3])};
;                     float part = (v[0] * v[0] + v[1] * v[1]) + (v[2] * v[2] + v[3] * v[3]);
;                     part = wave_sum(part, lane_);
;                     if (lane_ < 4) ssq_next[(size_t)(u.pm * 256 + ai * 128 + w8 * 16 + rr) * 16 + u.pn * 4 + lane_] = (lane_ == 0) ? part : 0.f;
;                 }
.LBB0_621:
	ds_read_b128 v[94:97], v0 offset:9360
	s_waitcnt lgkmcnt(0)
	v_pk_add_f32 v[90:91], v[90:91], v[94:95]
	v_add_co_u32_e32 v94, vcc, 0x9000, v136
	v_pk_add_f32 v[92:93], v[92:93], v[96:97]
	s_nop 0
	v_addc_co_u32_e32 v95, vcc, 0, v137, vcc
	s_and_b64 vcc, exec, s[6:7]
	global_store_dwordx4 v[94:95], v[90:93], off nt
	s_cbranch_vccnz .LBB0_625
	v_cvt_pk_bf16_f32 v94, v90, v91
	v_mul_f32_e32 v91, v91, v91
	v_fmac_f32_e32 v91, v90, v90
	v_mul_f32_e32 v90, v93, v93
	v_fmac_f32_e32 v90, v92, v92
	v_add_f32_e32 v90, v91, v90
	v_add_co_u32_e32 v96, vcc, 0x4000, v134
	s_nop 0
	v_add_f32_dpp v90, v90, v90 row_ror:1 row_mask:0xf bank_mask:0xf bound_ctrl:1
	v_cvt_pk_bf16_f32 v95, v92, v93
	v_addc_co_u32_e32 v97, vcc, 0, v135, vcc
	v_add_f32_dpp v90, v90, v90 row_ror:2 row_mask:0xf bank_mask:0xf bound_ctrl:1
	flat_store_dwordx2 v[96:97], v[94:95] offset:2048
	s_nop 0
	v_add_f32_dpp v90, v90, v90 row_ror:4 row_mask:0xf bank_mask:0xf bound_ctrl:1
	s_nop 1
	v_add_f32_dpp v90, v90, v90 row_ror:8 row_mask:0xf bank_mask:0xf bound_ctrl:1
	s_nop 0
	v_readlane_b32 s24, v90, 0
	v_readlane_b32 s2, v90, 16
	v_readlane_b32 s25, v90, 32
	v_readlane_b32 s3, v90, 48
	s_and_saveexec_b64 s[22:23], s[4:5]
	s_cbranch_execz .LBB0_624
	v_mov_b32_e32 v90, s2
	s_or_b32 s2, s18, 9
	v_mov_b32_e32 v91, s3
	s_ashr_i32 s3, s2, 31
	s_lshl_b64 s[2:3], s[2:3], 6
	s_add_u32 s19, s10, s2
	s_addc_u32 s20, s11, s3
	s_lshl_b64 s[2:3], s[16:17], 2
	v_pk_add_f32 v[90:91], s[24:25], v[90:91]
	s_add_u32 s2, s19, s2
	v_add_f32_e32 v90, v90, v91
	s_addc_u32 s3, s20, s3
	v_cndmask_b32_e64 v92, 0, v90, s[0:1]
	v_lshl_add_u64 v[90:91], v[130:131], 2, s[2:3]
	flat_store_dword v[90:91], v92

; #define LAS __attribute__((address_space(3)))
; DI unsigned pk2(float lo, float hi) { f32x2 v = {lo, hi}; return __builtin_bit_cast(unsigned, __builtin_convertvector(v, bf2_t)); }
;     DI void fused(const f32x4 (&acc)[2][2][4][2], const pg8::Unit& u, int wr, int wc, LAS unsigned char* lds) const {
;     ...
;             for (int rr = 0; rr < 16; ++rr) {
;                 const f32x4 a = *(const LAS f32x4*)(lds + (size_t)(w8 * 16 + rr) * 1040 + lane_ * 16);
;                 const f32x4 v = a + xo[rr];
;                 *(f32x4*)(xout + g0 + (size_t)rr * DM) = v;
;                 if (XB) {
;                     *(u32x2*)(XB + g0 + (size_t)rr * DM) = (u32x2){pk2(v[0], v[1]), pk2(v[2], v[3])};
;                     float part = (v[0] * v[0] + v[1] * v[1]) + (v[2] * v[2] + v[3] * v[3]);
;                     part = wave_sum(part, lane_);
;                     if (lane_ < 4) ssq_next[(size_t)(u.pm * 256 + ai * 128 + w8 * 16 + rr) * 16 + u.pn * 4 + lane_] = (lane_ == 0) ? part : 0.f;
;                 }
.LBB0_625:
	ds_read_b128 v[90:93], v0 offset:10400
	s_waitcnt lgkmcnt(0)
	v_pk_add_f32 v[86:87], v[86:87], v[90:91]
	v_add_co_u32_e32 v90, vcc, 0xa000, v136
	v_pk_add_f32 v[88:89], v[88:89], v[92:93]
	s_nop 0
	v_addc_co_u32_e32 v91, vcc, 0, v137, vcc
	s_and_b64 vcc, exec, s[6:7]
	global_store_dwordx4 v[90:91], v[86:89], off nt
	s_cbranch_vccnz .LBB0_629
	v_cvt_pk_bf16_f32 v90, v86, v87
	v_mul_f32_e32 v87, v87, v87
	v_fmac_f32_e32 v87, v86, v86
	v_mul_f32_e32 v86, v89, v89
	v_fmac_f32_e32 v86, v88, v88
	v_add_f32_e32 v86, v87, v86
	v_add_co_u32_e32 v92, vcc, 0x5000, v134
	s_nop 0
	v_add_f32_dpp v86, v86, v86 row_ror:1 row_mask:0xf bank_mask:0xf bound_ctrl:1
	v_cvt_pk_bf16_f32 v91, v88, v89
	v_addc_co_u32_e32 v93, vcc, 0, v135, vcc
	v_add_f32_dpp v86, v86, v86 row_ror:2 row_mask:0xf bank_mask:0xf bound_ctrl:1
	flat_store_dwordx2 v[92:93], v[90:91]
	s_nop 0
	v_add_f32_dpp v86, v86, v86 row_ror:4 row_mask:0xf bank_mask:0xf bound_ctrl:1
	s_nop 1
	v_add_f32_dpp v86, v86, v86 row_ror:8 row_mask:0xf bank_mask:0xf bound_ctrl:1
	s_nop 0
	v_readlane_b32 s24, v86, 0
	v_readlane_b32 s2, v86, 16
	v_readlane_b32 s25, v86, 32
	v_readlane_b32 s3, v86, 48
	s_and_saveexec_b64 s[22:23], s[4:5]
	s_cbranch_execz .LBB0_628
	v_mov_b32_e32 v86, s2
	s_or_b32 s2, s18, 10
	v_mov_b32_e32 v87, s3
	s_ashr_i32 s3, s2, 31
	s_lshl_b64 s[2:3], s[2:3], 6
	s_add_u32 s19, s10, s2
	s_addc_u32 s20, s11, s3
	s_lshl_b64 s[2:3], s[16:17], 2
	v_pk_add_f32 v[86:87], s[24:25], v[86:87]
	s_add_u32 s2, s19, s2
	v_add_f32_e32 v86, v86, v87
	s_addc_u32 s3, s20, s3
	v_cndmask_b32_e64 v88, 0, v86, s[0:1]
	v_lshl_add_u64 v[86:87], v[130:131], 2, s[2:3]
	flat_store_dword v[86:87], v88

; #define LAS __attribute__((address_space(3)))
; DI unsigned pk2(float lo, float hi) { f32x2 v = {lo, hi}; return __builtin_bit_cast(unsigned, __builtin_convertvector(v, bf2_t)); }
;     DI void fused(const f32x4 (&acc)[2][2][4][2], const pg8::Unit& u, int wr, int wc, LAS unsigned char* lds) const {
;     ...
;             for (int rr = 0; rr < 16; ++rr) {
;                 const f32x4 a = *(const LAS f32x4*)(lds + (size_t)(w8 * 16 + rr) * 1040 + lane_ * 16);
;                 const f32x4 v = a + xo[rr];
;                 *(f32x4*)(xout + g0 + (size_t)rr * DM) = v;
;                 if (XB) {
;                     *(u32x2*)(XB + g0 + (size_t)rr * DM) = (u32x2){pk2(v[0], v[1]), pk2(v[2], v[3])};
;                     float part = (v[0] * v[0] + v[1] * v[1]) + (v[2] * v[2] + v[3] * v[3]);
;                     part = wave_sum(part, lane_);
;                     if (lane_ < 4) ssq_next[(size_t)(u.pm * 256 + ai * 128 + w8 * 16 + rr) * 16 + u.pn * 4 + lane_] = (lane_ == 0) ? part : 0.f;
;                 }
.LBB0_629:
	ds_read_b128 v[86:89], v0 offset:11440
	s_waitcnt lgkmcnt(0)
	v_pk_add_f32 v[82:83], v[82:83], v[86:87]
	v_add_co_u32_e32 v86, vcc, 0xb000, v136
	v_pk_add_f32 v[84:85], v[84:85], v[88:89]
	s_nop 0
	v_addc_co_u32_e32 v87, vcc, 0, v137, vcc
	s_and_b64 vcc, exec, s[6:7]
	global_store_dwordx4 v[86:87], v[82:85], off nt
	s_cbranch_vccnz .LBB0_633
	v_cvt_pk_bf16_f32 v86, v82, v83
	v_mul_f32_e32 v83, v83, v83
	v_fmac_f32_e32 v83, v82, v82
	v_mul_f32_e32 v82, v85, v85
	v_fmac_f32_e32 v82, v84, v84
	v_add_f32_e32 v82, v83, v82
	v_add_co_u32_e32 v88, vcc, 0x5000, v134
	s_nop 0
	v_add_f32_dpp v82, v82, v82 row_ror:1 row_mask:0xf bank_mask:0xf bound_ctrl:1
	v_cvt_pk_bf16_f32 v87, v84, v85
	v_addc_co_u32_e32 v89, vcc, 0, v135, vcc
	v_add_f32_dpp v82, v82, v82 row_ror:2 row_mask:0xf bank_mask:0xf bound_ctrl:1
	flat_store_dwordx2 v[88:89], v[86:87] offset:2048
	s_nop 0
	v_add_f32_dpp v82, v82, v82 row_ror:4 row_mask:0xf bank_mask:0xf bound_ctrl:1
	s_nop 1
	v_add_f32_dpp v82, v82, v82 row_ror:8 row_mask:0xf bank_mask:0xf bound_ctrl:1
	s_nop 0
	v_readlane_b32 s24, v82, 0
	v_readlane_b32 s2, v82, 16
	v_readlane_b32 s25, v82, 32
	v_readlane_b32 s3, v82, 48
	s_and_saveexec_b64 s[22:23], s[4:5]
	s_cbranch_execz .LBB0_632
	v_mov_b32_e32 v82, s2
	s_or_b32 s2, s18, 11
	v_mov_b32_e32 v83, s3
	s_ashr_i32 s3, s2, 31
	s_lshl_b64 s[2:3], s[2:3], 6
	s_add_u32 s19, s10, s2
	s_addc_u32 s20, s11, s3
	s_lshl_b64 s[2:3], s[16:17], 2
	v_pk_add_f32 v[82:83], s[24:25], v[82:83]
	s_add_u32 s2, s19, s2
	v_add_f32_e32 v82, v82, v83
	s_addc_u32 s3, s20, s3
	v_cndmask_b32_e64 v84, 0, v82, s[0:1]
	v_lshl_add_u64 v[82:83], v[130:131], 2, s[2:3]
	flat_store_dword v[82:83], v84

; #define LAS __attribute__((address_space(3)))
; DI unsigned pk2(float lo, float hi) { f32x2 v = {lo, hi}; return __builtin_bit_cast(unsigned, __builtin_convertvector(v, bf2_t)); }
;     DI void fused(const f32x4 (&acc)[2][2][4][2], const pg8::Unit& u, int wr, int wc, LAS unsigned char* lds) const {
;     ...
;             for (int rr = 0; rr < 16; ++rr) {
;                 const f32x4 a = *(const LAS f32x4*)(lds + (size_t)(w8 * 16 + rr) * 1040 + lane_ * 16);
;                 const f32x4 v = a + xo[rr];
;                 *(f32x4*)(xout + g0 + (size_t)rr * DM) = v;
;                 if (XB) {
;                     *(u32x2*)(XB + g0 + (size_t)rr * DM) = (u32x2){pk2(v[0], v[1]), pk2(v[2], v[3])};
;                     float part = (v[0] * v[0] + v[1] * v[1]) + (v[2] * v[2] + v[3] * v[3]);
;                     part = wave_sum(part, lane_);
;                     if (lane_ < 4) ssq_next[(size_t)(u.pm * 256 + ai * 128 + w8 * 16 + rr) * 16 + u.pn * 4 + lane_] = (lane_ == 0) ? part : 0.f;
;                 }
.LBB0_633:
	ds_read_b128 v[82:85], v0 offset:12480
	s_waitcnt lgkmcnt(0)
	v_pk_add_f32 v[78:79], v[78:79], v[82:83]
	v_add_co_u32_e32 v82, vcc, 0xc000, v136
	v_pk_add_f32 v[80:81], v[80:81], v[84:85]
	s_nop 0
	v_addc_co_u32_e32 v83, vcc, 0, v137, vcc
	s_and_b64 vcc, exec, s[6:7]
	global_store_dwordx4 v[82:83], v[78:81], off nt
	s_cbranch_vccnz .LBB0_637
	v_cvt_pk_bf16_f32 v82, v78, v79
	v_mul_f32_e32 v79, v79, v79
	v_fmac_f32_e32 v79, v78, v78
	v_mul_f32_e32 v78, v81, v81
	v_fmac_f32_e32 v78, v80, v80
	v_add_f32_e32 v78, v79, v78
	v_add_co_u32_e32 v84, vcc, 0x6000, v134
	s_nop 0
	v_add_f32_dpp v78, v78, v78 row_ror:1 row_mask:0xf bank_mask:0xf bound_ctrl:1
	v_cvt_pk_bf16_f32 v83, v80, v81
	v_addc_co_u32_e32 v85, vcc, 0, v135, vcc
	v_add_f32_dpp v78, v78, v78 row_ror:2 row_mask:0xf bank_mask:0xf bound_ctrl:1
	flat_store_dwordx2 v[84:85], v[82:83]
	s_nop 0
	v_add_f32_dpp v78, v78, v78 row_ror:4 row_mask:0xf bank_mask:0xf bound_ctrl:1
	s_nop 1
	v_add_f32_dpp v78, v78, v78 row_ror:8 row_mask:0xf bank_mask:0xf bound_ctrl:1
	s_nop 0
	v_readlane_b32 s24, v78, 0
	v_readlane_b32 s2, v78, 16
	v_readlane_b32 s25, v78, 32
	v_readlane_b32 s3, v78, 48
	s_and_saveexec_b64 s[22:23], s[4:5]
	s_cbranch_execz .LBB0_636
	v_mov_b32_e32 v78, s2
	s_or_b32 s2, s18, 12
	v_mov_b32_e32 v79, s3
	s_ashr_i32 s3, s2, 31
	s_lshl_b64 s[2:3], s[2:3], 6
	s_add_u32 s19, s10, s2
	s_addc_u32 s20, s11, s3
	s_lshl_b64 s[2:3], s[16:17], 2
	v_pk_add_f32 v[78:79], s[24:25], v[78:79]
	s_add_u32 s2, s19, s2
	v_add_f32_e32 v78, v78, v79
	s_addc_u32 s3, s20, s3
	v_cndmask_b32_e64 v80, 0, v78, s[0:1]
	v_lshl_add_u64 v[78:79], v[130:131], 2, s[2:3]
	flat_store_dword v[78:79], v80

; #define LAS __attribute__((address_space(3)))
; DI unsigned pk2(float lo, float hi) { f32x2 v = {lo, hi}; return __builtin_bit_cast(unsigned, __builtin_convertvector(v, bf2_t)); }
;     DI void fused(const f32x4 (&acc)[2][2][4][2], const pg8::Unit& u, int wr, int wc, LAS unsigned char* lds) const {
;     ...
;             for (int rr = 0; rr < 16; ++rr) {
;                 const f32x4 a = *(const LAS f32x4*)(lds + (size_t)(w8 * 16 + rr) * 1040 + lane_ * 16);
;                 const f32x4 v = a + xo[rr];
;                 *(f32x4*)(xout + g0 + (size_t)rr * DM) = v;
;                 if (XB) {
;                     *(u32x2*)(XB + g0 + (size_t)rr * DM) = (u32x2){pk2(v[0], v[1]), pk2(v[2], v[3])};
;                     float part = (v[0] * v[0] + v[1] * v[1]) + (v[2] * v[2] + v[3] * v[3]);
;                     part = wave_sum(part, lane_);
;                     if (lane_ < 4) ssq_next[(size_t)(u.pm * 256 + ai * 128 + w8 * 16 + rr) * 16 + u.pn * 4 + lane_] = (lane_ == 0) ? part : 0.f;
;                 }
.LBB0_637:
	ds_read_b128 v[78:81], v0 offset:13520
	s_waitcnt lgkmcnt(0)
	v_pk_add_f32 v[74:75], v[74:75], v[78:79]
	v_add_co_u32_e32 v78, vcc, 0xd000, v136
	v_pk_add_f32 v[76:77], v[76:77], v[80:81]
	s_nop 0
	v_addc_co_u32_e32 v79, vcc, 0, v137, vcc
	s_and_b64 vcc, exec, s[6:7]
	global_store_dwordx4 v[78:79], v[74:77], off nt
	s_cbranch_vccnz .LBB0_641
	v_cvt_pk_bf16_f32 v78, v74, v75
	v_mul_f32_e32 v75, v75, v75
	v_fmac_f32_e32 v75, v74, v74
	v_mul_f32_e32 v74, v77, v77
	v_fmac_f32_e32 v74, v76, v76
	v_add_f32_e32 v74, v75, v74
	v_add_co_u32_e32 v80, vcc, 0x6000, v134
	s_nop 0
	v_add_f32_dpp v74, v74, v74 row_ror:1 row_mask:0xf bank_mask:0xf bound_ctrl:1
	v_cvt_pk_bf16_f32 v79, v76, v77
	v_addc_co_u32_e32 v81, vcc, 0, v135, vcc
	v_add_f32_dpp v74, v74, v74 row_ror:2 row_mask:0xf bank_mask:0xf bound_ctrl:1
	flat_store_dwordx2 v[80:81], v[78:79] offset:2048
	s_nop 0
	v_add_f32_dpp v74, v74, v74 row_ror:4 row_mask:0xf bank_mask:0xf bound_ctrl:1
	s_nop 1
	v_add_f32_dpp v74, v74, v74 row_ror:8 row_mask:0xf bank_mask:0xf bound_ctrl:1
	s_nop 0
	v_readlane_b32 s24, v74, 0
	v_readlane_b32 s2, v74, 16
	v_readlane_b32 s25, v74, 32
	v_readlane_b32 s3, v74, 48
	s_and_saveexec_b64 s[22:23], s[4:5]
	s_cbranch_execz .LBB0_640
	v_mov_b32_e32 v74, s2
	s_or_b32 s2, s18, 13
	v_mov_b32_e32 v75, s3
	s_ashr_i32 s3, s2, 31
	s_lshl_b64 s[2:3], s[2:3], 6
	s_add_u32 s19, s10, s2
	s_addc_u32 s20, s11, s3
	s_lshl_b64 s[2:3], s[16:17], 2
	v_pk_add_f32 v[74:75], s[24:25], v[74:75]
	s_add_u32 s2, s19, s2
	v_add_f32_e32 v74, v74, v75
	s_addc_u32 s3, s20, s3
	v_cndmask_b32_e64 v76, 0, v74, s[0:1]
	v_lshl_add_u64 v[74:75], v[130:131], 2, s[2:3]
	flat_store_dword v[74:75], v76

; #define LAS __attribute__((address_space(3)))
; DI unsigned pk2(float lo, float hi) { f32x2 v = {lo, hi}; return __builtin_bit_cast(unsigned, __builtin_convertvector(v, bf2_t)); }
;     DI void fused(const f32x4 (&acc)[2][2][4][2], const pg8::Unit& u, int wr, int wc, LAS unsigned char* lds) const {
;     ...
;             for (int rr = 0; rr < 16; ++rr) {
;                 const f32x4 a = *(const LAS f32x4*)(lds + (size_t)(w8 * 16 + rr) * 1040 + lane_ * 16);
;                 const f32x4 v = a + xo[rr];
;                 *(f32x4*)(xout + g0 + (size_t)rr * DM) = v;
;                 if (XB) {
;                     *(u32x2*)(XB + g0 + (size_t)rr * DM) = (u32x2){pk2(v[0], v[1]), pk2(v[2], v[3])};
;                     float part = (v[0] * v[0] + v[1] * v[1]) + (v[2] * v[2] + v[3] * v[3]);
;                     part = wave_sum(part, lane_);
;                     if (lane_ < 4) ssq_next[(size_t)(u.pm * 256 + ai * 128 + w8 * 16 + rr) * 16 + u.pn * 4 + lane_] = (lane_ == 0) ? part : 0.f;
;                 }
.LBB0_641:
	ds_read_b128 v[74:77], v0 offset:14560
	s_waitcnt lgkmcnt(0)
	v_pk_add_f32 v[70:71], v[70:71], v[74:75]
	v_add_co_u32_e32 v74, vcc, 0xe000, v136
	v_pk_add_f32 v[72:73], v[72:73], v[76:77]
	s_nop 0
	v_addc_co_u32_e32 v75, vcc, 0, v137, vcc
	s_and_b64 vcc, exec, s[6:7]
	global_store_dwordx4 v[74:75], v[70:73], off nt
	s_cbranch_vccnz .LBB0_645
	v_cvt_pk_bf16_f32 v74, v70, v71
	v_mul_f32_e32 v71, v71, v71
	v_fmac_f32_e32 v71, v70, v70
	v_mul_f32_e32 v70, v73, v73
	v_fmac_f32_e32 v70, v72, v72
	v_add_f32_e32 v70, v71, v70
	v_add_co_u32_e32 v76, vcc, 0x7000, v134
	s_nop 0
	v_add_f32_dpp v70, v70, v70 row_ror:1 row_mask:0xf bank_mask:0xf bound_ctrl:1
	v_cvt_pk_bf16_f32 v75, v72, v73
	v_addc_co_u32_e32 v77, vcc, 0, v135, vcc
	v_add_f32_dpp v70, v70, v70 row_ror:2 row_mask:0xf bank_mask:0xf bound_ctrl:1
	flat_store_dwordx2 v[76:77], v[74:75]
	s_nop 0
	v_add_f32_dpp v70, v70, v70 row_ror:4 row_mask:0xf bank_mask:0xf bound_ctrl:1
	s_nop 1
	v_add_f32_dpp v70, v70, v70 row_ror:8 row_mask:0xf bank_mask:0xf bound_ctrl:1
	s_nop 0
	v_readlane_b32 s24, v70, 0
	v_readlane_b32 s2, v70, 16
	v_readlane_b32 s25, v70, 32
	v_readlane_b32 s3, v70, 48
	s_and_saveexec_b64 s[22:23], s[4:5]
	s_cbranch_execz .LBB0_644
	v_mov_b32_e32 v70, s2
	s_or_b32 s2, s18, 14
	v_mov_b32_e32 v71, s3
	s_ashr_i32 s3, s2, 31
	s_lshl_b64 s[2:3], s[2:3], 6
	s_add_u32 s19, s10, s2
	s_addc_u32 s20, s11, s3
	s_lshl_b64 s[2:3], s[16:17], 2
	v_pk_add_f32 v[70:71], s[24:25], v[70:71]
	s_add_u32 s2, s19, s2
	v_add_f32_e32 v70, v70, v71
	s_addc_u32 s3, s20, s3
	v_cndmask_b32_e64 v72, 0, v70, s[0:1]
	v_lshl_add_u64 v[70:71], v[130:131], 2, s[2:3]
	flat_store_dword v[70:71], v72

; #define LAS __attribute__((address_space(3)))
; DI unsigned pk2(float lo, float hi) { f32x2 v = {lo, hi}; return __builtin_bit_cast(unsigned, __builtin_convertvector(v, bf2_t)); }
;     DI void fused(const f32x4 (&acc)[2][2][4][2], const pg8::Unit& u, int wr, int wc, LAS unsigned char* lds) const {
;     ...
;             for (int rr = 0; rr < 16; ++rr) {
;                 const f32x4 a = *(const LAS f32x4*)(lds + (size_t)(w8 * 16 + rr) * 1040 + lane_ * 16);
;                 const f32x4 v = a + xo[rr];
;                 *(f32x4*)(xout + g0 + (size_t)rr * DM) = v;
;                 if (XB) {
;                     *(u32x2*)(XB + g0 + (size_t)rr * DM) = (u32x2){pk2(v[0], v[1]), pk2(v[2], v[3])};
;                     float part = (v[0] * v[0] + v[1] * v[1]) + (v[2] * v[2] + v[3] * v[3]);
;                     part = wave_sum(part, lane_);
;                     if (lane_ < 4) ssq_next[(size_t)(u.pm * 256 + ai * 128 + w8 * 16 + rr) * 16 + u.pn * 4 + lane_] = (lane_ == 0) ? part : 0.f;
;                 }
.LBB0_645:
	ds_read_b128 v[70:73], v0 offset:15600
	s_waitcnt lgkmcnt(0)
	v_pk_add_f32 v[66:67], v[66:67], v[70:71]
	v_add_co_u32_e32 v70, vcc, 0xf000, v136
	v_pk_add_f32 v[68:69], v[68:69], v[72:73]
	s_nop 0
	v_addc_co_u32_e32 v71, vcc, 0, v137, vcc
	s_and_b64 vcc, exec, s[6:7]
	global_store_dwordx4 v[70:71], v[66:69], off nt
	s_cbranch_vccnz .LBB0_649
	v_cvt_pk_bf16_f32 v70, v66, v67
	v_mul_f32_e32 v67, v67, v67
	v_fmac_f32_e32 v67, v66, v66
	v_mul_f32_e32 v66, v69, v69
	v_fmac_f32_e32 v66, v68, v68
	v_add_f32_e32 v66, v67, v66
	v_add_co_u32_e32 v72, vcc, 0x7000, v134
	s_nop 0
	v_add_f32_dpp v66, v66, v66 row_ror:1 row_mask:0xf bank_mask:0xf bound_ctrl:1
	v_cvt_pk_bf16_f32 v71, v68, v69
	v_addc_co_u32_e32 v73, vcc, 0, v135, vcc
	v_add_f32_dpp v66, v66, v66 row_ror:2 row_mask:0xf bank_mask:0xf bound_ctrl:1
	flat_store_dwordx2 v[72:73], v[70:71] offset:2048
	s_nop 0
	v_add_f32_dpp v66, v66, v66 row_ror:4 row_mask:0xf bank_mask:0xf bound_ctrl:1
	s_nop 1
	v_add_f32_dpp v66, v66, v66 row_ror:8 row_mask:0xf bank_mask:0xf bound_ctrl:1
	s_nop 0
	v_readlane_b32 s24, v66, 0
	v_readlane_b32 s2, v66, 16
	v_readlane_b32 s25, v66, 32
	v_readlane_b32 s3, v66, 48
	s_and_saveexec_b64 s[22:23], s[4:5]
	s_cbranch_execz .LBB0_648
	v_mov_b32_e32 v66, s2
	s_or_b32 s2, s18, 15
	v_mov_b32_e32 v67, s3
	s_ashr_i32 s3, s2, 31
	s_lshl_b64 s[2:3], s[2:3], 6
	s_add_u32 s19, s10, s2
	s_addc_u32 s20, s11, s3
	s_lshl_b64 s[2:3], s[16:17], 2
	v_pk_add_f32 v[66:67], s[24:25], v[66:67]
	s_add_u32 s2, s19, s2
	v_add_f32_e32 v66, v66, v67
	s_addc_u32 s3, s20, s3
	v_cndmask_b32_e64 v68, 0, v66, s[0:1]
	v_lshl_add_u64 v[66:67], v[130:131], 2, s[2:3]
	flat_store_dword v[66:67], v68

; #define LAS __attribute__((address_space(3)))
; DI unsigned pk2(float lo, float hi) { f32x2 v = {lo, hi}; return __builtin_bit_cast(unsigned, __builtin_convertvector(v, bf2_t)); }
;     DI void fused(const f32x4 (&acc)[2][2][4][2], const pg8::Unit& u, int wr, int wc, LAS unsigned char* lds) const {
;     ...
;         for (int ai = 0; ai < 2; ++ai) {
; #pragma unroll
;             for (int m = 0; m < 4; ++m)
; #pragma unroll
;                 for (int bj = 0; bj < 2; ++bj)
; #pragma unroll
;                     for (int n = 0; n < 2; ++n)
;                         *(LAS f32x4*)(lds + (size_t)(wr * 64 + m * 16 + fr) * 1040 + (bj * 128 + wc * 32 + n * 16 + 4 * fq) * 4) = acc[ai][bj][m][n];
;             __syncthreads();
;             const size_t g0 = (size_t)(u.pm * 256 + ai * 128 + w8 * 16) * DM + u.pn * 256 + lane_ * 4;
;             f32x4 xo[16];
; #pragma unroll
;             for (int rr = 0; rr < 16; ++rr) xo[rr] = *(const f32x4*)(xin + g0 + (size_t)rr * DM);
; #pragma unroll
;             for (int rr = 0; rr < 16; ++rr) {
;                 const f32x4 a = *(const LAS f32x4*)(lds + (size_t)(w8 * 16 + rr) * 1040 + lane_ * 16);
;                 const f32x4 v = a + xo[rr];
;                 *(f32x4*)(xout + g0 + (size_t)rr * DM) = v;
;                 if (XB) {
;                     *(u32x2*)(XB + g0 + (size_t)rr * DM) = (u32x2){pk2(v[0], v[1]), pk2(v[2], v[3])};
;                     float part = (v[0] * v[0] + v[1] * v[1]) + (v[2] * v[2] + v[3] * v[3]);
;                     part = wave_sum(part, lane_);
;                     if (lane_ < 4) ssq_next[(size_t)(u.pm * 256 + ai * 128 + w8 * 16 + rr) * 16 + u.pn * 4 + lane_] = (lane_ == 0) ? part : 0.f;
;                 }
.LBB0_649:
	s_addk_i32 s18, 0x80
	s_ashr_i32 s19, s18, 31
	s_lshl_b64 s[2:3], s[18:19], 10
	v_lshl_add_u64 v[72:73], v[132:133], 0, s[2:3]
	v_lshlrev_b64 v[66:67], 2, v[72:73]
	s_waitcnt lgkmcnt(0)
	s_barrier
	ds_write_b128 v138, v[62:65]
	ds_write_b128 v138, v[58:61] offset:64
	ds_write_b128 v138, v[54:57] offset:512
	ds_write_b128 v138, v[50:53] offset:576
	ds_write_b128 v138, v[46:49] offset:16640
	ds_write_b128 v138, v[42:45] offset:16704
	ds_write_b128 v138, v[38:41] offset:17152
	ds_write_b128 v138, v[34:37] offset:17216
	ds_write_b128 v138, v[30:33] offset:33280
	ds_write_b128 v138, v[26:29] offset:33344
	ds_write_b128 v138, v[22:25] offset:33792
	ds_write_b128 v138, v[18:21] offset:33856
	ds_write_b128 v138, v[14:17] offset:49920
	ds_write_b128 v138, v[10:13] offset:49984
	ds_write_b128 v138, v[6:9] offset:50432
	ds_write_b128 v138, v[2:5] offset:50496
	v_lshl_add_u64 v[2:3], s[14:15], 0, v[66:67]
	v_add_co_u32_e32 v4, vcc, s80, v2
	s_waitcnt lgkmcnt(0)
	s_nop 0
	v_addc_co_u32_e32 v5, vcc, 0, v3, vcc
	s_barrier
	global_load_dwordx4 v[62:65], v[2:3], off nt
	global_load_dwordx4 v[58:61], v[4:5], off offset:-4096 nt
	global_load_dwordx4 v[54:57], v[4:5], off nt
	v_add_co_u32_e32 v4, vcc, s81, v2
	s_movk_i32 s2, 0x6000
	s_nop 0
	v_addc_co_u32_e32 v5, vcc, 0, v3, vcc
	global_load_dwordx4 v[50:53], v[4:5], off offset:-4096 nt
	global_load_dwordx4 v[46:49], v[4:5], off nt
	v_add_co_u32_e32 v4, vcc, s2, v2
	s_mov_b32 s2, 0x8000
	s_nop 0
	v_addc_co_u32_e32 v5, vcc, 0, v3, vcc
	global_load_dwordx4 v[42:45], v[4:5], off offset:-4096 nt
	global_load_dwordx4 v[38:41], v[4:5], off nt
	v_add_co_u32_e32 v4, vcc, s2, v2
	s_mov_b32 s2, 0xa000
	s_nop 0
	v_addc_co_u32_e32 v5, vcc, 0, v3, vcc
	global_load_dwordx4 v[34:37], v[4:5], off offset:-4096 nt
	global_load_dwordx4 v[30:33], v[4:5], off nt
	v_add_co_u32_e32 v4, vcc, s2, v2
	s_mov_b32 s2, 0xc000
	s_nop 0
	v_addc_co_u32_e32 v5, vcc, 0, v3, vcc
	global_load_dwordx4 v[26:29], v[4:5], off offset:-4096 nt
	global_load_dwordx4 v[22:25], v[4:5], off nt
	v_add_co_u32_e32 v4, vcc, s2, v2
	s_mov_b32 s2, 0xe000
	s_nop 0
	v_addc_co_u32_e32 v5, vcc, 0, v3, vcc
	global_load_dwordx4 v[18:21], v[4:5], off offset:-4096 nt
	global_load_dwordx4 v[14:17], v[4:5], off nt
	v_add_co_u32_e32 v4, vcc, s2, v2
	s_mov_b32 s2, 0xf000
	s_nop 0
	v_addc_co_u32_e32 v5, vcc, 0, v3, vcc
	v_add_co_u32_e32 v2, vcc, s2, v2
	global_load_dwordx4 v[10:13], v[4:5], off offset:-4096 nt
	global_load_dwordx4 v[6:9], v[4:5], off nt
	v_addc_co_u32_e32 v3, vcc, 0, v3, vcc
	global_load_dwordx4 v[2:5], v[2:3], off nt
	ds_read_b128 v[68:71], v0
	s_mov_b64 s[14:15], -1
	v_lshl_add_u64 v[66:67], s[48:49], 0, v[66:67]
	s_and_b64 vcc, exec, s[6:7]
	s_waitcnt vmcnt(0) lgkmcnt(0)
	v_pk_add_f32 v[64:65], v[64:65], v[70:71]
	v_pk_add_f32 v[62:63], v[62:63], v[68:69]
	v_lshl_add_u64 v[68:69], v[72:73], 1, s[12:13]
	global_store_dwordx4 v[66:67], v[62:65], off nt
	s_cbranch_vccnz .LBB0_655
	v_cvt_pk_bf16_f32 v70, v62, v63
	v_mul_f32_e32 v63, v63, v63
	v_fmac_f32_e32 v63, v62, v62
	v_mul_f32_e32 v62, v65, v65
	v_fmac_f32_e32 v62, v64, v64
	v_add_f32_e32 v62, v63, v62
	v_cvt_pk_bf16_f32 v71, v64, v65
	flat_store_dwordx2 v[68:69], v[70:71]
	v_add_f32_dpp v62, v62, v62 row_ror:1 row_mask:0xf bank_mask:0xf bound_ctrl:1
	s_nop 1
	v_add_f32_dpp v62, v62, v62 row_ror:2 row_mask:0xf bank_mask:0xf bound_ctrl:1
	s_nop 1
	v_add_f32_dpp v62, v62, v62 row_ror:4 row_mask:0xf bank_mask:0xf bound_ctrl:1
	s_nop 1
	v_add_f32_dpp v62, v62, v62 row_ror:8 row_mask:0xf bank_mask:0xf bound_ctrl:1
	s_nop 0
	v_readlane_b32 s14, v62, 0
	v_readlane_b32 s2, v62, 16
	v_readlane_b32 s15, v62, 32
	v_readlane_b32 s3, v62, 48
	s_and_saveexec_b64 s[12:13], s[4:5]
	s_cbranch_execz .LBB0_652
	v_mov_b32_e32 v62, s2
	v_mov_b32_e32 v63, s3
	s_lshl_b64 s[2:3], s[18:19], 6
	v_pk_add_f32 v[62:63], s[14:15], v[62:63]
	s_add_u32 s14, s10, s2
	s_addc_u32 s15, s11, s3
	s_lshl_b64 s[2:3], s[16:17], 2
	s_add_u32 s2, s14, s2
	v_add_f32_e32 v62, v62, v63
	s_addc_u32 s3, s15, s3
	v_cndmask_b32_e64 v64, 0, v62, s[0:1]
	v_lshl_add_u64 v[62:63], v[130:131], 2, s[2:3]
	flat_store_dword v[62:63], v64
.LBB0_652:
	s_or_b64 exec, exec, s[12:13]
	ds_read_b128 v[62:65], v0 offset:1040
	v_add_co_u32_e32 v70, vcc, 0x1000, v66
	s_waitcnt lgkmcnt(0)
	v_pk_add_f32 v[64:65], v[60:61], v[64:65]
	v_pk_add_f32 v[62:63], v[58:59], v[62:63]
	v_addc_co_u32_e32 v71, vcc, 0, v67, vcc
	global_store_dwordx4 v[70:71], v[62:65], off nt
	v_cvt_pk_bf16_f32 v70, v62, v63
	v_cvt_pk_bf16_f32 v71, v64, v65
	v_mul_f32_e32 v63, v63, v63
	v_fmac_f32_e32 v63, v62, v62
	v_mul_f32_e32 v62, v65, v65
	v_fmac_f32_e32 v62, v64, v64
	v_add_f32_e32 v62, v63, v62
	flat_store_dwordx2 v[68:69], v[70:71] offset:2048
	s_nop 0
	v_add_f32_dpp v62, v62, v62 row_ror:1 row_mask:0xf bank_mask:0xf bound_ctrl:1
	s_nop 1
	v_add_f32_dpp v62, v62, v62 row_ror:2 row_mask:0xf bank_mask:0xf bound_ctrl:1
	s_nop 1
	v_add_f32_dpp v62, v62, v62 row_ror:4 row_mask:0xf bank_mask:0xf bound_ctrl:1
	s_nop 1
	v_add_f32_dpp v62, v62, v62 row_ror:8 row_mask:0xf bank_mask:0xf bound_ctrl:1
	s_nop 0
	v_readlane_b32 s14, v62, 0
	v_readlane_b32 s2, v62, 16
	v_readlane_b32 s15, v62, 32
	v_readlane_b32 s3, v62, 48
	s_and_saveexec_b64 s[12:13], s[4:5]
	s_cbranch_execz .LBB0_654
	v_mov_b32_e32 v62, s2
	s_or_b32 s2, s18, 1
	v_mov_b32_e32 v63, s3
	s_ashr_i32 s3, s2, 31
	s_lshl_b64 s[2:3], s[2:3], 6
	v_pk_add_f32 v[62:63], s[14:15], v[62:63]
	s_add_u32 s14, s10, s2
	s_addc_u32 s15, s11, s3
	s_lshl_b64 s[2:3], s[16:17], 2
	s_add_u32 s2, s14, s2
	v_add_f32_e32 v62, v62, v63
	s_addc_u32 s3, s15, s3
	v_cndmask_b32_e64 v64, 0, v62, s[0:1]
	v_lshl_add_u64 v[62:63], v[130:131], 2, s[2:3]
	flat_store_dword v[62:63], v64

; #define LAS __attribute__((address_space(3)))
; DI unsigned pk2(float lo, float hi) { f32x2 v = {lo, hi}; return __builtin_bit_cast(unsigned, __builtin_convertvector(v, bf2_t)); }
;     DI void fused(const f32x4 (&acc)[2][2][4][2], const pg8::Unit& u, int wr, int wc, LAS unsigned char* lds) const {
;     ...
;             for (int rr = 0; rr < 16; ++rr) {
;                 const f32x4 a = *(const LAS f32x4*)(lds + (size_t)(w8 * 16 + rr) * 1040 + lane_ * 16);
;                 const f32x4 v = a + xo[rr];
;                 *(f32x4*)(xout + g0 + (size_t)rr * DM) = v;
;                 if (XB) {
;                     *(u32x2*)(XB + g0 + (size_t)rr * DM) = (u32x2){pk2(v[0], v[1]), pk2(v[2], v[3])};
;                     float part = (v[0] * v[0] + v[1] * v[1]) + (v[2] * v[2] + v[3] * v[3]);
;                     part = wave_sum(part, lane_);
;                     if (lane_ < 4) ssq_next[(size_t)(u.pm * 256 + ai * 128 + w8 * 16 + rr) * 16 + u.pn * 4 + lane_] = (lane_ == 0) ? part : 0.f;
;                 }
.LBB0_655:
	s_and_b64 vcc, exec, s[14:15]
	s_cbranch_vccz .LBB0_657
	ds_read_b128 v[62:65], v0 offset:1040
	s_waitcnt lgkmcnt(0)
	v_pk_add_f32 v[58:59], v[58:59], v[62:63]
	v_add_co_u32_e32 v62, vcc, 0x1000, v66
	v_pk_add_f32 v[60:61], v[60:61], v[64:65]
	s_nop 0
	v_addc_co_u32_e32 v63, vcc, 0, v67, vcc
	global_store_dwordx4 v[62:63], v[58:61], off nt
.LBB0_657:
	ds_read_b128 v[58:61], v0 offset:2080
	s_mov_b64 s[12:13], -1
	s_waitcnt lgkmcnt(0)
	v_pk_add_f32 v[54:55], v[54:55], v[58:59]
	v_add_co_u32_e32 v58, vcc, 0x2000, v66
	v_pk_add_f32 v[56:57], v[56:57], v[60:61]
	s_nop 0
	v_addc_co_u32_e32 v59, vcc, 0, v67, vcc
	s_and_b64 vcc, exec, s[6:7]
	global_store_dwordx4 v[58:59], v[54:57], off nt
	s_cbranch_vccnz .LBB0_663
	v_cvt_pk_bf16_f32 v58, v54, v55
	v_mul_f32_e32 v55, v55, v55
	v_fmac_f32_e32 v55, v54, v54
	v_mul_f32_e32 v54, v57, v57
	v_fmac_f32_e32 v54, v56, v56
	v_add_f32_e32 v54, v55, v54
	v_add_co_u32_e32 v60, vcc, 0x1000, v68
	s_nop 0
	v_add_f32_dpp v54, v54, v54 row_ror:1 row_mask:0xf bank_mask:0xf bound_ctrl:1
	v_cvt_pk_bf16_f32 v59, v56, v57
	v_addc_co_u32_e32 v61, vcc, 0, v69, vcc
	v_add_f32_dpp v54, v54, v54 row_ror:2 row_mask:0xf bank_mask:0xf bound_ctrl:1
	flat_store_dwordx2 v[60:61], v[58:59]
	s_nop 0
	v_add_f32_dpp v54, v54, v54 row_ror:4 row_mask:0xf bank_mask:0xf bound_ctrl:1
	s_nop 1
	v_add_f32_dpp v54, v54, v54 row_ror:8 row_mask:0xf bank_mask:0xf bound_ctrl:1
	s_nop 0
	v_readlane_b32 s14, v54, 0
	v_readlane_b32 s2, v54, 16
	v_readlane_b32 s15, v54, 32
	v_readlane_b32 s3, v54, 48
	s_and_saveexec_b64 s[12:13], s[4:5]
	s_cbranch_execz .LBB0_660
	v_mov_b32_e32 v54, s2
	s_or_b32 s2, s18, 2
	v_mov_b32_e32 v55, s3
	s_ashr_i32 s3, s2, 31
	s_lshl_b64 s[2:3], s[2:3], 6
	v_pk_add_f32 v[54:55], s[14:15], v[54:55]
	s_add_u32 s14, s10, s2
	s_addc_u32 s15, s11, s3
	s_lshl_b64 s[2:3], s[16:17], 2
	s_add_u32 s2, s14, s2
	v_add_f32_e32 v54, v54, v55
	s_addc_u32 s3, s15, s3
	v_cndmask_b32_e64 v56, 0, v54, s[0:1]
	v_lshl_add_u64 v[54:55], v[130:131], 2, s[2:3]
	flat_store_dword v[54:55], v56
.LBB0_660:
	s_or_b64 exec, exec, s[12:13]
	ds_read_b128 v[54:57], v0 offset:3120
	v_add_co_u32_e32 v58, vcc, 0x3000, v66
	s_movk_i32 s2, 0x1000
	s_nop 0
	v_addc_co_u32_e32 v59, vcc, 0, v67, vcc
	s_waitcnt lgkmcnt(0)
	v_pk_add_f32 v[56:57], v[52:53], v[56:57]
	v_pk_add_f32 v[54:55], v[50:51], v[54:55]
	global_store_dwordx4 v[58:59], v[54:57], off nt
	v_cvt_pk_bf16_f32 v58, v54, v55
	v_add_co_u32_e32 v60, vcc, s2, v68
	v_mul_f32_e32 v55, v55, v55
	v_fmac_f32_e32 v55, v54, v54
	v_mul_f32_e32 v54, v57, v57
	v_fmac_f32_e32 v54, v56, v56
	v_add_f32_e32 v54, v55, v54
	v_cvt_pk_bf16_f32 v59, v56, v57
	v_addc_co_u32_e32 v61, vcc, 0, v69, vcc
	v_add_f32_dpp v54, v54, v54 row_ror:1 row_mask:0xf bank_mask:0xf bound_ctrl:1
	flat_store_dwordx2 v[60:61], v[58:59] offset:2048
	s_nop 0
	v_add_f32_dpp v54, v54, v54 row_ror:2 row_mask:0xf bank_mask:0xf bound_ctrl:1
	s_nop 1
	v_add_f32_dpp v54, v54, v54 row_ror:4 row_mask:0xf bank_mask:0xf bound_ctrl:1
	s_nop 1
	v_add_f32_dpp v54, v54, v54 row_ror:8 row_mask:0xf bank_mask:0xf bound_ctrl:1
	s_nop 0
	v_readlane_b32 s14, v54, 0
	v_readlane_b32 s2, v54, 16
	v_readlane_b32 s15, v54, 32
	v_readlane_b32 s3, v54, 48
	s_and_saveexec_b64 s[12:13], s[4:5]
	s_cbranch_execz .LBB0_662
	v_mov_b32_e32 v54, s2
	s_or_b32 s2, s18, 3
	v_mov_b32_e32 v55, s3
	s_ashr_i32 s3, s2, 31
	s_lshl_b64 s[2:3], s[2:3], 6
	v_pk_add_f32 v[54:55], s[14:15], v[54:55]
	s_add_u32 s14, s10, s2
	s_addc_u32 s15, s11, s3
	s_lshl_b64 s[2:3], s[16:17], 2
	s_add_u32 s2, s14, s2
	v_add_f32_e32 v54, v54, v55
	s_addc_u32 s3, s15, s3
	v_cndmask_b32_e64 v56, 0, v54, s[0:1]
	v_lshl_add_u64 v[54:55], v[130:131], 2, s[2:3]
	flat_store_dword v[54:55], v56

; #define LAS __attribute__((address_space(3)))
; DI unsigned pk2(float lo, float hi) { f32x2 v = {lo, hi}; return __builtin_bit_cast(unsigned, __builtin_convertvector(v, bf2_t)); }
;     DI void fused(const f32x4 (&acc)[2][2][4][2], const pg8::Unit& u, int wr, int wc, LAS unsigned char* lds) const {
;     ...
;             for (int rr = 0; rr < 16; ++rr) {
;                 const f32x4 a = *(const LAS f32x4*)(lds + (size_t)(w8 * 16 + rr) * 1040 + lane_ * 16);
;                 const f32x4 v = a + xo[rr];
;                 *(f32x4*)(xout + g0 + (size_t)rr * DM) = v;
;                 if (XB) {
;                     *(u32x2*)(XB + g0 + (size_t)rr * DM) = (u32x2){pk2(v[0], v[1]), pk2(v[2], v[3])};
;                     float part = (v[0] * v[0] + v[1] * v[1]) + (v[2] * v[2] + v[3] * v[3]);
;                     part = wave_sum(part, lane_);
;                     if (lane_ < 4) ssq_next[(size_t)(u.pm * 256 + ai * 128 + w8 * 16 + rr) * 16 + u.pn * 4 + lane_] = (lane_ == 0) ? part : 0.f;
;                 }
.LBB0_663:
	s_and_b64 vcc, exec, s[12:13]
	s_cbranch_vccz .LBB0_665
	ds_read_b128 v[54:57], v0 offset:3120
	s_waitcnt lgkmcnt(0)
	v_pk_add_f32 v[50:51], v[50:51], v[54:55]
	v_add_co_u32_e32 v54, vcc, 0x3000, v66
	v_pk_add_f32 v[52:53], v[52:53], v[56:57]
	s_nop 0
	v_addc_co_u32_e32 v55, vcc, 0, v67, vcc
	global_store_dwordx4 v[54:55], v[50:53], off nt
.LBB0_665:
	ds_read_b128 v[50:53], v0 offset:4160
	s_mov_b64 s[12:13], -1
	s_waitcnt lgkmcnt(0)
	v_pk_add_f32 v[46:47], v[46:47], v[50:51]
	v_add_co_u32_e32 v50, vcc, 0x4000, v66
	v_pk_add_f32 v[48:49], v[48:49], v[52:53]
	s_nop 0
	v_addc_co_u32_e32 v51, vcc, 0, v67, vcc
	s_and_b64 vcc, exec, s[6:7]
	global_store_dwordx4 v[50:51], v[46:49], off nt
	s_cbranch_vccnz .LBB0_671
	v_cvt_pk_bf16_f32 v50, v46, v47
	v_mul_f32_e32 v47, v47, v47
	v_fmac_f32_e32 v47, v46, v46
	v_mul_f32_e32 v46, v49, v49
	v_fmac_f32_e32 v46, v48, v48
	v_add_f32_e32 v46, v47, v46
	v_add_co_u32_e32 v52, vcc, 0x2000, v68
	s_nop 0
	v_add_f32_dpp v46, v46, v46 row_ror:1 row_mask:0xf bank_mask:0xf bound_ctrl:1
	v_cvt_pk_bf16_f32 v51, v48, v49
	v_addc_co_u32_e32 v53, vcc, 0, v69, vcc
	v_add_f32_dpp v46, v46, v46 row_ror:2 row_mask:0xf bank_mask:0xf bound_ctrl:1
	flat_store_dwordx2 v[52:53], v[50:51]
	s_nop 0
	v_add_f32_dpp v46, v46, v46 row_ror:4 row_mask:0xf bank_mask:0xf bound_ctrl:1
	s_nop 1
	v_add_f32_dpp v46, v46, v46 row_ror:8 row_mask:0xf bank_mask:0xf bound_ctrl:1
	s_nop 0
	v_readlane_b32 s14, v46, 0
	v_readlane_b32 s2, v46, 16
	v_readlane_b32 s15, v46, 32
	v_readlane_b32 s3, v46, 48
	s_and_saveexec_b64 s[12:13], s[4:5]
	s_cbranch_execz .LBB0_668
	v_mov_b32_e32 v46, s2
	s_or_b32 s2, s18, 4
	v_mov_b32_e32 v47, s3
	s_ashr_i32 s3, s2, 31
	s_lshl_b64 s[2:3], s[2:3], 6
	v_pk_add_f32 v[46:47], s[14:15], v[46:47]
	s_add_u32 s14, s10, s2
	s_addc_u32 s15, s11, s3
	s_lshl_b64 s[2:3], s[16:17], 2
	s_add_u32 s2, s14, s2
	v_add_f32_e32 v46, v46, v47
	s_addc_u32 s3, s15, s3
	v_cndmask_b32_e64 v48, 0, v46, s[0:1]
	v_lshl_add_u64 v[46:47], v[130:131], 2, s[2:3]
	flat_store_dword v[46:47], v48
.LBB0_668:
	s_or_b64 exec, exec, s[12:13]
	ds_read_b128 v[46:49], v0 offset:5200
	v_add_co_u32_e32 v50, vcc, 0x5000, v66
	s_waitcnt lgkmcnt(0)
	v_pk_add_f32 v[48:49], v[44:45], v[48:49]
	v_pk_add_f32 v[46:47], v[42:43], v[46:47]
	v_addc_co_u32_e32 v51, vcc, 0, v67, vcc
	global_store_dwordx4 v[50:51], v[46:49], off nt
	v_cvt_pk_bf16_f32 v50, v46, v47
	v_add_co_u32_e32 v52, vcc, s80, v68
	v_mul_f32_e32 v47, v47, v47
	v_fmac_f32_e32 v47, v46, v46
	v_mul_f32_e32 v46, v49, v49
	v_fmac_f32_e32 v46, v48, v48
	v_add_f32_e32 v46, v47, v46
	v_cvt_pk_bf16_f32 v51, v48, v49
	v_addc_co_u32_e32 v53, vcc, 0, v69, vcc
	v_add_f32_dpp v46, v46, v46 row_ror:1 row_mask:0xf bank_mask:0xf bound_ctrl:1
	flat_store_dwordx2 v[52:53], v[50:51] offset:2048
	s_nop 0
	v_add_f32_dpp v46, v46, v46 row_ror:2 row_mask:0xf bank_mask:0xf bound_ctrl:1
	s_nop 1
	v_add_f32_dpp v46, v46, v46 row_ror:4 row_mask:0xf bank_mask:0xf bound_ctrl:1
	s_nop 1
	v_add_f32_dpp v46, v46, v46 row_ror:8 row_mask:0xf bank_mask:0xf bound_ctrl:1
	s_nop 0
	v_readlane_b32 s14, v46, 0
	v_readlane_b32 s2, v46, 16
	v_readlane_b32 s15, v46, 32
	v_readlane_b32 s3, v46, 48
	s_and_saveexec_b64 s[12:13], s[4:5]
	s_cbranch_execz .LBB0_670
	v_mov_b32_e32 v46, s2
	s_or_b32 s2, s18, 5
	v_mov_b32_e32 v47, s3
	s_ashr_i32 s3, s2, 31
	s_lshl_b64 s[2:3], s[2:3], 6
	v_pk_add_f32 v[46:47], s[14:15], v[46:47]
	s_add_u32 s14, s10, s2
	s_addc_u32 s15, s11, s3
	s_lshl_b64 s[2:3], s[16:17], 2
	s_add_u32 s2, s14, s2
	v_add_f32_e32 v46, v46, v47
	s_addc_u32 s3, s15, s3
	v_cndmask_b32_e64 v48, 0, v46, s[0:1]
	v_lshl_add_u64 v[46:47], v[130:131], 2, s[2:3]
	flat_store_dword v[46:47], v48

; #define LAS __attribute__((address_space(3)))
; DI unsigned pk2(float lo, float hi) { f32x2 v = {lo, hi}; return __builtin_bit_cast(unsigned, __builtin_convertvector(v, bf2_t)); }
;     DI void fused(const f32x4 (&acc)[2][2][4][2], const pg8::Unit& u, int wr, int wc, LAS unsigned char* lds) const {
;     ...
;             for (int rr = 0; rr < 16; ++rr) {
;                 const f32x4 a = *(const LAS f32x4*)(lds + (size_t)(w8 * 16 + rr) * 1040 + lane_ * 16);
;                 const f32x4 v = a + xo[rr];
;                 *(f32x4*)(xout + g0 + (size_t)rr * DM) = v;
;                 if (XB) {
;                     *(u32x2*)(XB + g0 + (size_t)rr * DM) = (u32x2){pk2(v[0], v[1]), pk2(v[2], v[3])};
;                     float part = (v[0] * v[0] + v[1] * v[1]) + (v[2] * v[2] + v[3] * v[3]);
;                     part = wave_sum(part, lane_);
;                     if (lane_ < 4) ssq_next[(size_t)(u.pm * 256 + ai * 128 + w8 * 16 + rr) * 16 + u.pn * 4 + lane_] = (lane_ == 0) ? part : 0.f;
;                 }
.LBB0_671:
	s_and_b64 vcc, exec, s[12:13]
	s_cbranch_vccz .LBB0_673
	ds_read_b128 v[46:49], v0 offset:5200
	s_waitcnt lgkmcnt(0)
	v_pk_add_f32 v[42:43], v[42:43], v[46:47]
	v_add_co_u32_e32 v46, vcc, 0x5000, v66
	v_pk_add_f32 v[44:45], v[44:45], v[48:49]
	s_nop 0
	v_addc_co_u32_e32 v47, vcc, 0, v67, vcc
	global_store_dwordx4 v[46:47], v[42:45], off nt
.LBB0_673:
	ds_read_b128 v[42:45], v0 offset:6240
	s_mov_b64 s[12:13], -1
	s_waitcnt lgkmcnt(0)
	v_pk_add_f32 v[38:39], v[38:39], v[42:43]
	v_add_co_u32_e32 v42, vcc, 0x6000, v66
	v_pk_add_f32 v[40:41], v[40:41], v[44:45]
	s_nop 0
	v_addc_co_u32_e32 v43, vcc, 0, v67, vcc
	s_and_b64 vcc, exec, s[6:7]
	global_store_dwordx4 v[42:43], v[38:41], off nt
	s_cbranch_vccnz .LBB0_679
	v_cvt_pk_bf16_f32 v42, v38, v39
	v_mul_f32_e32 v39, v39, v39
	v_fmac_f32_e32 v39, v38, v38
	v_mul_f32_e32 v38, v41, v41
	v_fmac_f32_e32 v38, v40, v40
	v_add_f32_e32 v38, v39, v38
	v_add_co_u32_e32 v44, vcc, 0x3000, v68
	s_nop 0
	v_add_f32_dpp v38, v38, v38 row_ror:1 row_mask:0xf bank_mask:0xf bound_ctrl:1
	v_cvt_pk_bf16_f32 v43, v40, v41
	v_addc_co_u32_e32 v45, vcc, 0, v69, vcc
	v_add_f32_dpp v38, v38, v38 row_ror:2 row_mask:0xf bank_mask:0xf bound_ctrl:1
	flat_store_dwordx2 v[44:45], v[42:43]
	s_nop 0
	v_add_f32_dpp v38, v38, v38 row_ror:4 row_mask:0xf bank_mask:0xf bound_ctrl:1
	s_nop 1
	v_add_f32_dpp v38, v38, v38 row_ror:8 row_mask:0xf bank_mask:0xf bound_ctrl:1
	s_nop 0
	v_readlane_b32 s14, v38, 0
	v_readlane_b32 s2, v38, 16
	v_readlane_b32 s15, v38, 32
	v_readlane_b32 s3, v38, 48
	s_and_saveexec_b64 s[12:13], s[4:5]
	s_cbranch_execz .LBB0_676
	v_mov_b32_e32 v38, s2
	s_or_b32 s2, s18, 6
	v_mov_b32_e32 v39, s3
	s_ashr_i32 s3, s2, 31
	s_lshl_b64 s[2:3], s[2:3], 6
	v_pk_add_f32 v[38:39], s[14:15], v[38:39]
	s_add_u32 s14, s10, s2
	s_addc_u32 s15, s11, s3
	s_lshl_b64 s[2:3], s[16:17], 2
	s_add_u32 s2, s14, s2
	v_add_f32_e32 v38, v38, v39
	s_addc_u32 s3, s15, s3
	v_cndmask_b32_e64 v40, 0, v38, s[0:1]
	v_lshl_add_u64 v[38:39], v[130:131], 2, s[2:3]
	flat_store_dword v[38:39], v40
.LBB0_676:
	s_or_b64 exec, exec, s[12:13]
	ds_read_b128 v[38:41], v0 offset:7280
	v_add_co_u32_e32 v42, vcc, 0x7000, v66
	s_movk_i32 s2, 0x3000
	s_nop 0
	v_addc_co_u32_e32 v43, vcc, 0, v67, vcc
	s_waitcnt lgkmcnt(0)
	v_pk_add_f32 v[40:41], v[36:37], v[40:41]
	v_pk_add_f32 v[38:39], v[34:35], v[38:39]
	global_store_dwordx4 v[42:43], v[38:41], off nt
	v_cvt_pk_bf16_f32 v42, v38, v39
	v_add_co_u32_e32 v44, vcc, s2, v68
	v_mul_f32_e32 v39, v39, v39
	v_fmac_f32_e32 v39, v38, v38
	v_mul_f32_e32 v38, v41, v41
	v_fmac_f32_e32 v38, v40, v40
	v_add_f32_e32 v38, v39, v38
	v_cvt_pk_bf16_f32 v43, v40, v41
	v_addc_co_u32_e32 v45, vcc, 0, v69, vcc
	v_add_f32_dpp v38, v38, v38 row_ror:1 row_mask:0xf bank_mask:0xf bound_ctrl:1
	flat_store_dwordx2 v[44:45], v[42:43] offset:2048
	s_nop 0
	v_add_f32_dpp v38, v38, v38 row_ror:2 row_mask:0xf bank_mask:0xf bound_ctrl:1
	s_nop 1
	v_add_f32_dpp v38, v38, v38 row_ror:4 row_mask:0xf bank_mask:0xf bound_ctrl:1
	s_nop 1
	v_add_f32_dpp v38, v38, v38 row_ror:8 row_mask:0xf bank_mask:0xf bound_ctrl:1
	s_nop 0
	v_readlane_b32 s14, v38, 0
	v_readlane_b32 s2, v38, 16
	v_readlane_b32 s15, v38, 32
	v_readlane_b32 s3, v38, 48
	s_and_saveexec_b64 s[12:13], s[4:5]
	s_cbranch_execz .LBB0_678
	v_mov_b32_e32 v38, s2
	s_or_b32 s2, s18, 7
	v_mov_b32_e32 v39, s3
	s_ashr_i32 s3, s2, 31
	s_lshl_b64 s[2:3], s[2:3], 6
	v_pk_add_f32 v[38:39], s[14:15], v[38:39]
	s_add_u32 s14, s10, s2
	s_addc_u32 s15, s11, s3
	s_lshl_b64 s[2:3], s[16:17], 2
	s_add_u32 s2, s14, s2
	v_add_f32_e32 v38, v38, v39
	s_addc_u32 s3, s15, s3
	v_cndmask_b32_e64 v40, 0, v38, s[0:1]
	v_lshl_add_u64 v[38:39], v[130:131], 2, s[2:3]
	flat_store_dword v[38:39], v40

; #define LAS __attribute__((address_space(3)))
; DI unsigned pk2(float lo, float hi) { f32x2 v = {lo, hi}; return __builtin_bit_cast(unsigned, __builtin_convertvector(v, bf2_t)); }
;     DI void fused(const f32x4 (&acc)[2][2][4][2], const pg8::Unit& u, int wr, int wc, LAS unsigned char* lds) const {
;     ...
;             for (int rr = 0; rr < 16; ++rr) {
;                 const f32x4 a = *(const LAS f32x4*)(lds + (size_t)(w8 * 16 + rr) * 1040 + lane_ * 16);
;                 const f32x4 v = a + xo[rr];
;                 *(f32x4*)(xout + g0 + (size_t)rr * DM) = v;
;                 if (XB) {
;                     *(u32x2*)(XB + g0 + (size_t)rr * DM) = (u32x2){pk2(v[0], v[1]), pk2(v[2], v[3])};
;                     float part = (v[0] * v[0] + v[1] * v[1]) + (v[2] * v[2] + v[3] * v[3]);
;                     part = wave_sum(part, lane_);
;                     if (lane_ < 4) ssq_next[(size_t)(u.pm * 256 + ai * 128 + w8 * 16 + rr) * 16 + u.pn * 4 + lane_] = (lane_ == 0) ? part : 0.f;
;                 }
.LBB0_679:
	s_and_b64 vcc, exec, s[12:13]
	s_cbranch_vccz .LBB0_681
	ds_read_b128 v[38:41], v0 offset:7280
	s_waitcnt lgkmcnt(0)
	v_pk_add_f32 v[34:35], v[34:35], v[38:39]
	v_add_co_u32_e32 v38, vcc, 0x7000, v66
	v_pk_add_f32 v[36:37], v[36:37], v[40:41]
	s_nop 0
	v_addc_co_u32_e32 v39, vcc, 0, v67, vcc
	global_store_dwordx4 v[38:39], v[34:37], off nt
.LBB0_681:
	ds_read_b128 v[34:37], v0 offset:8320
	s_mov_b64 s[12:13], -1
	s_waitcnt lgkmcnt(0)
	v_pk_add_f32 v[30:31], v[30:31], v[34:35]
	v_add_co_u32_e32 v34, vcc, 0x8000, v66
	v_pk_add_f32 v[32:33], v[32:33], v[36:37]
	s_nop 0
	v_addc_co_u32_e32 v35, vcc, 0, v67, vcc
	s_and_b64 vcc, exec, s[6:7]
	global_store_dwordx4 v[34:35], v[30:33], off nt
	s_cbranch_vccnz .LBB0_687
	v_cvt_pk_bf16_f32 v34, v30, v31
	v_mul_f32_e32 v31, v31, v31
	v_fmac_f32_e32 v31, v30, v30
	v_mul_f32_e32 v30, v33, v33
	v_fmac_f32_e32 v30, v32, v32
	v_add_f32_e32 v30, v31, v30
	v_add_co_u32_e32 v36, vcc, 0x4000, v68
	s_nop 0
	v_add_f32_dpp v30, v30, v30 row_ror:1 row_mask:0xf bank_mask:0xf bound_ctrl:1
	v_cvt_pk_bf16_f32 v35, v32, v33
	v_addc_co_u32_e32 v37, vcc, 0, v69, vcc
	v_add_f32_dpp v30, v30, v30 row_ror:2 row_mask:0xf bank_mask:0xf bound_ctrl:1
	flat_store_dwordx2 v[36:37], v[34:35]
	s_nop 0
	v_add_f32_dpp v30, v30, v30 row_ror:4 row_mask:0xf bank_mask:0xf bound_ctrl:1
	s_nop 1
	v_add_f32_dpp v30, v30, v30 row_ror:8 row_mask:0xf bank_mask:0xf bound_ctrl:1
	s_nop 0
	v_readlane_b32 s14, v30, 0
	v_readlane_b32 s2, v30, 16
	v_readlane_b32 s15, v30, 32
	v_readlane_b32 s3, v30, 48
	s_and_saveexec_b64 s[12:13], s[4:5]
	s_cbranch_execz .LBB0_684
	v_mov_b32_e32 v30, s2
	s_or_b32 s2, s18, 8
	v_mov_b32_e32 v31, s3
	s_ashr_i32 s3, s2, 31
	s_lshl_b64 s[2:3], s[2:3], 6
	v_pk_add_f32 v[30:31], s[14:15], v[30:31]
	s_add_u32 s14, s10, s2
	s_addc_u32 s15, s11, s3
	s_lshl_b64 s[2:3], s[16:17], 2
	s_add_u32 s2, s14, s2
	v_add_f32_e32 v30, v30, v31
	s_addc_u32 s3, s15, s3
	v_cndmask_b32_e64 v32, 0, v30, s[0:1]
	v_lshl_add_u64 v[30:31], v[130:131], 2, s[2:3]
	flat_store_dword v[30:31], v32
.LBB0_684:
	s_or_b64 exec, exec, s[12:13]
	ds_read_b128 v[30:33], v0 offset:9360
	v_add_co_u32_e32 v34, vcc, 0x9000, v66
	s_waitcnt lgkmcnt(0)
	v_pk_add_f32 v[32:33], v[28:29], v[32:33]
	v_pk_add_f32 v[30:31], v[26:27], v[30:31]
	v_addc_co_u32_e32 v35, vcc, 0, v67, vcc
	global_store_dwordx4 v[34:35], v[30:33], off nt
	v_cvt_pk_bf16_f32 v34, v30, v31
	v_add_co_u32_e32 v36, vcc, s81, v68
	v_mul_f32_e32 v31, v31, v31
	v_fmac_f32_e32 v31, v30, v30
	v_mul_f32_e32 v30, v33, v33
	v_fmac_f32_e32 v30, v32, v32
	v_add_f32_e32 v30, v31, v30
	v_cvt_pk_bf16_f32 v35, v32, v33
	v_addc_co_u32_e32 v37, vcc, 0, v69, vcc
	v_add_f32_dpp v30, v30, v30 row_ror:1 row_mask:0xf bank_mask:0xf bound_ctrl:1
	flat_store_dwordx2 v[36:37], v[34:35] offset:2048
	s_nop 0
	v_add_f32_dpp v30, v30, v30 row_ror:2 row_mask:0xf bank_mask:0xf bound_ctrl:1
	s_nop 1
	v_add_f32_dpp v30, v30, v30 row_ror:4 row_mask:0xf bank_mask:0xf bound_ctrl:1
	s_nop 1
	v_add_f32_dpp v30, v30, v30 row_ror:8 row_mask:0xf bank_mask:0xf bound_ctrl:1
	s_nop 0
	v_readlane_b32 s14, v30, 0
	v_readlane_b32 s2, v30, 16
	v_readlane_b32 s15, v30, 32
	v_readlane_b32 s3, v30, 48
	s_and_saveexec_b64 s[12:13], s[4:5]
	s_cbranch_execz .LBB0_686
	v_mov_b32_e32 v30, s2
	s_or_b32 s2, s18, 9
	v_mov_b32_e32 v31, s3
	s_ashr_i32 s3, s2, 31
	s_lshl_b64 s[2:3], s[2:3], 6
	v_pk_add_f32 v[30:31], s[14:15], v[30:31]
	s_add_u32 s14, s10, s2
	s_addc_u32 s15, s11, s3
	s_lshl_b64 s[2:3], s[16:17], 2
	s_add_u32 s2, s14, s2
	v_add_f32_e32 v30, v30, v31
	s_addc_u32 s3, s15, s3
	v_cndmask_b32_e64 v32, 0, v30, s[0:1]
	v_lshl_add_u64 v[30:31], v[130:131], 2, s[2:3]
	flat_store_dword v[30:31], v32

; #define LAS __attribute__((address_space(3)))
; DI unsigned pk2(float lo, float hi) { f32x2 v = {lo, hi}; return __builtin_bit_cast(unsigned, __builtin_convertvector(v, bf2_t)); }
;     DI void fused(const f32x4 (&acc)[2][2][4][2], const pg8::Unit& u, int wr, int wc, LAS unsigned char* lds) const {
;     ...
;             for (int rr = 0; rr < 16; ++rr) {
;                 const f32x4 a = *(const LAS f32x4*)(lds + (size_t)(w8 * 16 + rr) * 1040 + lane_ * 16);
;                 const f32x4 v = a + xo[rr];
;                 *(f32x4*)(xout + g0 + (size_t)rr * DM) = v;
;                 if (XB) {
;                     *(u32x2*)(XB + g0 + (size_t)rr * DM) = (u32x2){pk2(v[0], v[1]), pk2(v[2], v[3])};
;                     float part = (v[0] * v[0] + v[1] * v[1]) + (v[2] * v[2] + v[3] * v[3]);
;                     part = wave_sum(part, lane_);
;                     if (lane_ < 4) ssq_next[(size_t)(u.pm * 256 + ai * 128 + w8 * 16 + rr) * 16 + u.pn * 4 + lane_] = (lane_ == 0) ? part : 0.f;
;                 }
.LBB0_687:
	s_and_b64 vcc, exec, s[12:13]
	s_cbranch_vccz .LBB0_689
	ds_read_b128 v[30:33], v0 offset:9360
	s_waitcnt lgkmcnt(0)
	v_pk_add_f32 v[26:27], v[26:27], v[30:31]
	v_add_co_u32_e32 v30, vcc, 0x9000, v66
	v_pk_add_f32 v[28:29], v[28:29], v[32:33]
	s_nop 0
	v_addc_co_u32_e32 v31, vcc, 0, v67, vcc
	global_store_dwordx4 v[30:31], v[26:29], off nt
.LBB0_689:
	ds_read_b128 v[26:29], v0 offset:10400
	s_mov_b64 s[12:13], -1
	s_waitcnt lgkmcnt(0)
	v_pk_add_f32 v[22:23], v[22:23], v[26:27]
	v_add_co_u32_e32 v26, vcc, 0xa000, v66
	v_pk_add_f32 v[24:25], v[24:25], v[28:29]
	s_nop 0
	v_addc_co_u32_e32 v27, vcc, 0, v67, vcc
	s_and_b64 vcc, exec, s[6:7]
	global_store_dwordx4 v[26:27], v[22:25], off nt
	s_cbranch_vccnz .LBB0_695
	v_cvt_pk_bf16_f32 v26, v22, v23
	v_mul_f32_e32 v23, v23, v23
	v_fmac_f32_e32 v23, v22, v22
	v_mul_f32_e32 v22, v25, v25
	v_fmac_f32_e32 v22, v24, v24
	v_add_f32_e32 v22, v23, v22
	v_add_co_u32_e32 v28, vcc, 0x5000, v68
	s_nop 0
	v_add_f32_dpp v22, v22, v22 row_ror:1 row_mask:0xf bank_mask:0xf bound_ctrl:1
	v_cvt_pk_bf16_f32 v27, v24, v25
	v_addc_co_u32_e32 v29, vcc, 0, v69, vcc
	v_add_f32_dpp v22, v22, v22 row_ror:2 row_mask:0xf bank_mask:0xf bound_ctrl:1
	flat_store_dwordx2 v[28:29], v[26:27]
	s_nop 0
	v_add_f32_dpp v22, v22, v22 row_ror:4 row_mask:0xf bank_mask:0xf bound_ctrl:1
	s_nop 1
	v_add_f32_dpp v22, v22, v22 row_ror:8 row_mask:0xf bank_mask:0xf bound_ctrl:1
	s_nop 0
	v_readlane_b32 s14, v22, 0
	v_readlane_b32 s2, v22, 16
	v_readlane_b32 s15, v22, 32
	v_readlane_b32 s3, v22, 48
	s_and_saveexec_b64 s[12:13], s[4:5]
	s_cbranch_execz .LBB0_692
	v_mov_b32_e32 v22, s2
	s_or_b32 s2, s18, 10
	v_mov_b32_e32 v23, s3
	s_ashr_i32 s3, s2, 31
	s_lshl_b64 s[2:3], s[2:3], 6
	v_pk_add_f32 v[22:23], s[14:15], v[22:23]
	s_add_u32 s14, s10, s2
	s_addc_u32 s15, s11, s3
	s_lshl_b64 s[2:3], s[16:17], 2
	s_add_u32 s2, s14, s2
	v_add_f32_e32 v22, v22, v23
	s_addc_u32 s3, s15, s3
	v_cndmask_b32_e64 v24, 0, v22, s[0:1]
	v_lshl_add_u64 v[22:23], v[130:131], 2, s[2:3]
	flat_store_dword v[22:23], v24
.LBB0_692:
	s_or_b64 exec, exec, s[12:13]
	ds_read_b128 v[22:25], v0 offset:11440
	v_add_co_u32_e32 v26, vcc, 0xb000, v66
	s_movk_i32 s2, 0x5000
	s_nop 0
	v_addc_co_u32_e32 v27, vcc, 0, v67, vcc
	s_waitcnt lgkmcnt(0)
	v_pk_add_f32 v[24:25], v[20:21], v[24:25]
	v_pk_add_f32 v[22:23], v[18:19], v[22:23]
	global_store_dwordx4 v[26:27], v[22:25], off nt
	v_cvt_pk_bf16_f32 v26, v22, v23
	v_add_co_u32_e32 v28, vcc, s2, v68
	v_mul_f32_e32 v23, v23, v23
	v_fmac_f32_e32 v23, v22, v22
	v_mul_f32_e32 v22, v25, v25
	v_fmac_f32_e32 v22, v24, v24
	v_add_f32_e32 v22, v23, v22
	v_cvt_pk_bf16_f32 v27, v24, v25
	v_addc_co_u32_e32 v29, vcc, 0, v69, vcc
	v_add_f32_dpp v22, v22, v22 row_ror:1 row_mask:0xf bank_mask:0xf bound_ctrl:1
	flat_store_dwordx2 v[28:29], v[26:27] offset:2048
	s_nop 0
	v_add_f32_dpp v22, v22, v22 row_ror:2 row_mask:0xf bank_mask:0xf bound_ctrl:1
	s_nop 1
	v_add_f32_dpp v22, v22, v22 row_ror:4 row_mask:0xf bank_mask:0xf bound_ctrl:1
	s_nop 1
	v_add_f32_dpp v22, v22, v22 row_ror:8 row_mask:0xf bank_mask:0xf bound_ctrl:1
	s_nop 0
	v_readlane_b32 s14, v22, 0
	v_readlane_b32 s2, v22, 16
	v_readlane_b32 s15, v22, 32
	v_readlane_b32 s3, v22, 48
	s_and_saveexec_b64 s[12:13], s[4:5]
	s_cbranch_execz .LBB0_694
	v_mov_b32_e32 v22, s2
	s_or_b32 s2, s18, 11
	v_mov_b32_e32 v23, s3
	s_ashr_i32 s3, s2, 31
	s_lshl_b64 s[2:3], s[2:3], 6
	v_pk_add_f32 v[22:23], s[14:15], v[22:23]
	s_add_u32 s14, s10, s2
	s_addc_u32 s15, s11, s3
	s_lshl_b64 s[2:3], s[16:17], 2
	s_add_u32 s2, s14, s2
	v_add_f32_e32 v22, v22, v23
	s_addc_u32 s3, s15, s3
	v_cndmask_b32_e64 v24, 0, v22, s[0:1]
	v_lshl_add_u64 v[22:23], v[130:131], 2, s[2:3]
	flat_store_dword v[22:23], v24

; #define LAS __attribute__((address_space(3)))
; DI unsigned pk2(float lo, float hi) { f32x2 v = {lo, hi}; return __builtin_bit_cast(unsigned, __builtin_convertvector(v, bf2_t)); }
;     DI void fused(const f32x4 (&acc)[2][2][4][2], const pg8::Unit& u, int wr, int wc, LAS unsigned char* lds) const {
;     ...
;             for (int rr = 0; rr < 16; ++rr) {
;                 const f32x4 a = *(const LAS f32x4*)(lds + (size_t)(w8 * 16 + rr) * 1040 + lane_ * 16);
;                 const f32x4 v = a + xo[rr];
;                 *(f32x4*)(xout + g0 + (size_t)rr * DM) = v;
;                 if (XB) {
;                     *(u32x2*)(XB + g0 + (size_t)rr * DM) = (u32x2){pk2(v[0], v[1]), pk2(v[2], v[3])};
;                     float part = (v[0] * v[0] + v[1] * v[1]) + (v[2] * v[2] + v[3] * v[3]);
;                     part = wave_sum(part, lane_);
;                     if (lane_ < 4) ssq_next[(size_t)(u.pm * 256 + ai * 128 + w8 * 16 + rr) * 16 + u.pn * 4 + lane_] = (lane_ == 0) ? part : 0.f;
;                 }
.LBB0_695:
	s_and_b64 vcc, exec, s[12:13]
	s_cbranch_vccz .LBB0_697
	ds_read_b128 v[22:25], v0 offset:11440
	s_waitcnt lgkmcnt(0)
	v_pk_add_f32 v[18:19], v[18:19], v[22:23]
	v_add_co_u32_e32 v22, vcc, 0xb000, v66
	v_pk_add_f32 v[20:21], v[20:21], v[24:25]
	s_nop 0
	v_addc_co_u32_e32 v23, vcc, 0, v67, vcc
	global_store_dwordx4 v[22:23], v[18:21], off nt
.LBB0_697:
	ds_read_b128 v[18:21], v0 offset:12480
	s_mov_b64 s[12:13], -1
	s_waitcnt lgkmcnt(0)
	v_pk_add_f32 v[14:15], v[14:15], v[18:19]
	v_add_co_u32_e32 v18, vcc, 0xc000, v66
	v_pk_add_f32 v[16:17], v[16:17], v[20:21]
	s_nop 0
	v_addc_co_u32_e32 v19, vcc, 0, v67, vcc
	s_and_b64 vcc, exec, s[6:7]
	global_store_dwordx4 v[18:19], v[14:17], off nt
	s_cbranch_vccnz .LBB0_703
	v_cvt_pk_bf16_f32 v18, v14, v15
	v_mul_f32_e32 v15, v15, v15
	v_fmac_f32_e32 v15, v14, v14
	v_mul_f32_e32 v14, v17, v17
	v_fmac_f32_e32 v14, v16, v16
	v_add_f32_e32 v14, v15, v14
	v_add_co_u32_e32 v20, vcc, 0x6000, v68
	s_nop 0
	v_add_f32_dpp v14, v14, v14 row_ror:1 row_mask:0xf bank_mask:0xf bound_ctrl:1
	v_cvt_pk_bf16_f32 v19, v16, v17
	v_addc_co_u32_e32 v21, vcc, 0, v69, vcc
	v_add_f32_dpp v14, v14, v14 row_ror:2 row_mask:0xf bank_mask:0xf bound_ctrl:1
	flat_store_dwordx2 v[20:21], v[18:19]
	s_nop 0
	v_add_f32_dpp v14, v14, v14 row_ror:4 row_mask:0xf bank_mask:0xf bound_ctrl:1
	s_nop 1
	v_add_f32_dpp v14, v14, v14 row_ror:8 row_mask:0xf bank_mask:0xf bound_ctrl:1
	s_nop 0
	v_readlane_b32 s14, v14, 0
	v_readlane_b32 s2, v14, 16
	v_readlane_b32 s15, v14, 32
	v_readlane_b32 s3, v14, 48
	s_and_saveexec_b64 s[12:13], s[4:5]
	s_cbranch_execz .LBB0_700
	v_mov_b32_e32 v14, s2
	s_or_b32 s2, s18, 12
	v_mov_b32_e32 v15, s3
	s_ashr_i32 s3, s2, 31
	s_lshl_b64 s[2:3], s[2:3], 6
	v_pk_add_f32 v[14:15], s[14:15], v[14:15]
	s_add_u32 s14, s10, s2
	s_addc_u32 s15, s11, s3
	s_lshl_b64 s[2:3], s[16:17], 2
	s_add_u32 s2, s14, s2
	v_add_f32_e32 v14, v14, v15
	s_addc_u32 s3, s15, s3
	v_cndmask_b32_e64 v16, 0, v14, s[0:1]
	v_lshl_add_u64 v[14:15], v[130:131], 2, s[2:3]
	flat_store_dword v[14:15], v16
.LBB0_700:
	s_or_b64 exec, exec, s[12:13]
	ds_read_b128 v[14:17], v0 offset:13520
	v_add_co_u32_e32 v18, vcc, 0xd000, v66
	s_movk_i32 s2, 0x6000
	s_nop 0
	v_addc_co_u32_e32 v19, vcc, 0, v67, vcc
	s_waitcnt lgkmcnt(0)
	v_pk_add_f32 v[16:17], v[12:13], v[16:17]
	v_pk_add_f32 v[14:15], v[10:11], v[14:15]
	global_store_dwordx4 v[18:19], v[14:17], off nt
	v_cvt_pk_bf16_f32 v18, v14, v15
	v_add_co_u32_e32 v20, vcc, s2, v68
	v_mul_f32_e32 v15, v15, v15
	v_fmac_f32_e32 v15, v14, v14
	v_mul_f32_e32 v14, v17, v17
	v_fmac_f32_e32 v14, v16, v16
	v_add_f32_e32 v14, v15, v14
	v_cvt_pk_bf16_f32 v19, v16, v17
	v_addc_co_u32_e32 v21, vcc, 0, v69, vcc
	v_add_f32_dpp v14, v14, v14 row_ror:1 row_mask:0xf bank_mask:0xf bound_ctrl:1
	flat_store_dwordx2 v[20:21], v[18:19] offset:2048
	s_nop 0
	v_add_f32_dpp v14, v14, v14 row_ror:2 row_mask:0xf bank_mask:0xf bound_ctrl:1
	s_nop 1
	v_add_f32_dpp v14, v14, v14 row_ror:4 row_mask:0xf bank_mask:0xf bound_ctrl:1
	s_nop 1
	v_add_f32_dpp v14, v14, v14 row_ror:8 row_mask:0xf bank_mask:0xf bound_ctrl:1
	s_nop 0
	v_readlane_b32 s14, v14, 0
	v_readlane_b32 s2, v14, 16
	v_readlane_b32 s15, v14, 32
	v_readlane_b32 s3, v14, 48
	s_and_saveexec_b64 s[12:13], s[4:5]
	s_cbranch_execz .LBB0_702
	v_mov_b32_e32 v14, s2
	s_or_b32 s2, s18, 13
	v_mov_b32_e32 v15, s3
	s_ashr_i32 s3, s2, 31
	s_lshl_b64 s[2:3], s[2:3], 6
	v_pk_add_f32 v[14:15], s[14:15], v[14:15]
	s_add_u32 s14, s10, s2
	s_addc_u32 s15, s11, s3
	s_lshl_b64 s[2:3], s[16:17], 2
	s_add_u32 s2, s14, s2
	v_add_f32_e32 v14, v14, v15
	s_addc_u32 s3, s15, s3
	v_cndmask_b32_e64 v16, 0, v14, s[0:1]
	v_lshl_add_u64 v[14:15], v[130:131], 2, s[2:3]
	flat_store_dword v[14:15], v16

; #define LAS __attribute__((address_space(3)))
; DI unsigned pk2(float lo, float hi) { f32x2 v = {lo, hi}; return __builtin_bit_cast(unsigned, __builtin_convertvector(v, bf2_t)); }
;     DI void fused(const f32x4 (&acc)[2][2][4][2], const pg8::Unit& u, int wr, int wc, LAS unsigned char* lds) const {
;     ...
;             for (int rr = 0; rr < 16; ++rr) {
;                 const f32x4 a = *(const LAS f32x4*)(lds + (size_t)(w8 * 16 + rr) * 1040 + lane_ * 16);
;                 const f32x4 v = a + xo[rr];
;                 *(f32x4*)(xout + g0 + (size_t)rr * DM) = v;
;                 if (XB) {
;                     *(u32x2*)(XB + g0 + (size_t)rr * DM) = (u32x2){pk2(v[0], v[1]), pk2(v[2], v[3])};
;                     float part = (v[0] * v[0] + v[1] * v[1]) + (v[2] * v[2] + v[3] * v[3]);
;                     part = wave_sum(part, lane_);
;                     if (lane_ < 4) ssq_next[(size_t)(u.pm * 256 + ai * 128 + w8 * 16 + rr) * 16 + u.pn * 4 + lane_] = (lane_ == 0) ? part : 0.f;
;                 }
.LBB0_703:
	s_and_b64 vcc, exec, s[12:13]
	s_cbranch_vccz .LBB0_705
	ds_read_b128 v[14:17], v0 offset:13520
	s_waitcnt lgkmcnt(0)
	v_pk_add_f32 v[10:11], v[10:11], v[14:15]
	v_add_co_u32_e32 v14, vcc, 0xd000, v66
	v_pk_add_f32 v[12:13], v[12:13], v[16:17]
	s_nop 0
	v_addc_co_u32_e32 v15, vcc, 0, v67, vcc
	global_store_dwordx4 v[14:15], v[10:13], off nt
.LBB0_705:
	ds_read_b128 v[10:13], v0 offset:14560
	s_mov_b64 s[12:13], -1
	s_waitcnt lgkmcnt(0)
	v_pk_add_f32 v[6:7], v[6:7], v[10:11]
	v_add_co_u32_e32 v10, vcc, 0xe000, v66
	v_pk_add_f32 v[8:9], v[8:9], v[12:13]
	s_nop 0
	v_addc_co_u32_e32 v11, vcc, 0, v67, vcc
	s_and_b64 vcc, exec, s[6:7]
	global_store_dwordx4 v[10:11], v[6:9], off nt
	s_cbranch_vccnz .LBB0_713
	v_cvt_pk_bf16_f32 v10, v6, v7
	v_mul_f32_e32 v7, v7, v7
	v_fmac_f32_e32 v7, v6, v6
	v_mul_f32_e32 v6, v9, v9
	v_fmac_f32_e32 v6, v8, v8
	v_add_f32_e32 v6, v7, v6
	v_add_co_u32_e32 v12, vcc, 0x7000, v68
	s_nop 0
	v_add_f32_dpp v6, v6, v6 row_ror:1 row_mask:0xf bank_mask:0xf bound_ctrl:1
	v_cvt_pk_bf16_f32 v11, v8, v9
	v_addc_co_u32_e32 v13, vcc, 0, v69, vcc
	v_add_f32_dpp v6, v6, v6 row_ror:2 row_mask:0xf bank_mask:0xf bound_ctrl:1
	flat_store_dwordx2 v[12:13], v[10:11]
	s_nop 0
	v_add_f32_dpp v6, v6, v6 row_ror:4 row_mask:0xf bank_mask:0xf bound_ctrl:1
	s_nop 1
	v_add_f32_dpp v6, v6, v6 row_ror:8 row_mask:0xf bank_mask:0xf bound_ctrl:1
	s_nop 0
	v_readlane_b32 s14, v6, 0
	v_readlane_b32 s2, v6, 16
	v_readlane_b32 s15, v6, 32
	v_readlane_b32 s3, v6, 48
	s_and_saveexec_b64 s[12:13], s[4:5]
	s_cbranch_execz .LBB0_708
	v_mov_b32_e32 v6, s2
	s_or_b32 s2, s18, 14
	v_mov_b32_e32 v7, s3
	s_ashr_i32 s3, s2, 31
	s_lshl_b64 s[2:3], s[2:3], 6
	v_pk_add_f32 v[6:7], s[14:15], v[6:7]
	s_add_u32 s14, s10, s2
	s_addc_u32 s15, s11, s3
	s_lshl_b64 s[2:3], s[16:17], 2
	s_add_u32 s2, s14, s2
	v_add_f32_e32 v6, v6, v7
	s_addc_u32 s3, s15, s3
	v_cndmask_b32_e64 v8, 0, v6, s[0:1]
	v_lshl_add_u64 v[6:7], v[130:131], 2, s[2:3]
	flat_store_dword v[6:7], v8
.LBB0_708:
	s_or_b64 exec, exec, s[12:13]
	ds_read_b128 v[6:9], v0 offset:15600
	v_add_co_u32_e32 v10, vcc, 0xf000, v66
	s_waitcnt lgkmcnt(0)
	v_pk_add_f32 v[8:9], v[4:5], v[8:9]
	v_addc_co_u32_e32 v11, vcc, 0, v67, vcc
	v_pk_add_f32 v[6:7], v[2:3], v[6:7]
	s_and_b64 vcc, exec, s[6:7]
	global_store_dwordx4 v[10:11], v[6:9], off nt
	s_cbranch_vccnz .LBB0_712
	v_cvt_pk_bf16_f32 v10, v6, v7
	v_mul_f32_e32 v7, v7, v7
	v_fmac_f32_e32 v7, v6, v6
	v_mul_f32_e32 v6, v9, v9
	v_fmac_f32_e32 v6, v8, v8
	v_add_f32_e32 v6, v7, v6
	v_add_co_u32_e32 v12, vcc, 0x7000, v68
	s_nop 0
	v_add_f32_dpp v6, v6, v6 row_ror:1 row_mask:0xf bank_mask:0xf bound_ctrl:1
	v_cvt_pk_bf16_f32 v11, v8, v9
	v_addc_co_u32_e32 v13, vcc, 0, v69, vcc
	v_add_f32_dpp v6, v6, v6 row_ror:2 row_mask:0xf bank_mask:0xf bound_ctrl:1
	flat_store_dwordx2 v[12:13], v[10:11] offset:2048
	s_nop 0
	v_add_f32_dpp v6, v6, v6 row_ror:4 row_mask:0xf bank_mask:0xf bound_ctrl:1
	s_nop 1
	v_add_f32_dpp v6, v6, v6 row_ror:8 row_mask:0xf bank_mask:0xf bound_ctrl:1
	s_nop 0
	v_readlane_b32 s12, v6, 0
	v_readlane_b32 s2, v6, 16
	v_readlane_b32 s13, v6, 32
	v_readlane_b32 s3, v6, 48
	s_and_saveexec_b64 s[6:7], s[4:5]
	s_cbranch_execz .LBB0_711
	v_mov_b32_e32 v6, s2
	v_mov_b32_e32 v7, s3
	v_pk_add_f32 v[6:7], s[12:13], v[6:7]
	s_nop 0
	v_add_f32_e32 v6, v6, v7
	v_cndmask_b32_e64 v8, 0, v6, s[0:1]
	s_or_b32 s0, s18, 15
	s_ashr_i32 s1, s0, 31
	s_lshl_b64 s[0:1], s[0:1], 6
	s_add_u32 s2, s10, s0
	s_addc_u32 s3, s11, s1
	s_lshl_b64 s[0:1], s[16:17], 2
	s_add_u32 s0, s2, s0
	s_addc_u32 s1, s3, s1
	v_lshl_add_u64 v[6:7], v[130:131], 2, s[0:1]
	flat_store_dword v[6:7], v8

; #define LAS __attribute__((address_space(3)))
; DI unsigned pk2(float lo, float hi) { f32x2 v = {lo, hi}; return __builtin_bit_cast(unsigned, __builtin_convertvector(v, bf2_t)); }
;     DI void fused(const f32x4 (&acc)[2][2][4][2], const pg8::Unit& u, int wr, int wc, LAS unsigned char* lds) const {
;     ...
;             for (int rr = 0; rr < 16; ++rr) {
;                 const f32x4 a = *(const LAS f32x4*)(lds + (size_t)(w8 * 16 + rr) * 1040 + lane_ * 16);
;                 const f32x4 v = a + xo[rr];
;                 *(f32x4*)(xout + g0 + (size_t)rr * DM) = v;
;                 if (XB) {
;                     *(u32x2*)(XB + g0 + (size_t)rr * DM) = (u32x2){pk2(v[0], v[1]), pk2(v[2], v[3])};
;                     float part = (v[0] * v[0] + v[1] * v[1]) + (v[2] * v[2] + v[3] * v[3]);
;                     part = wave_sum(part, lane_);
;                     if (lane_ < 4) ssq_next[(size_t)(u.pm * 256 + ai * 128 + w8 * 16 + rr) * 16 + u.pn * 4 + lane_] = (lane_ == 0) ? part : 0.f;
;                 }
.LBB0_713:
	s_and_b64 vcc, exec, s[12:13]
	s_cbranch_vccz .LBB0_715
	ds_read_b128 v[6:9], v0 offset:15600
	s_waitcnt lgkmcnt(0)
	v_pk_add_f32 v[2:3], v[2:3], v[6:7]
	v_add_co_u32_e32 v6, vcc, 0xf000, v66
	v_pk_add_f32 v[4:5], v[4:5], v[8:9]
	s_nop 0
	v_addc_co_u32_e32 v7, vcc, 0, v67, vcc
	global_store_dwordx4 v[6:7], v[2:5], off nt
